# stack2 = v40 + GEMM DMA pieces in SGPR-base form + attention-loop no-op s_nop/s_waitcnt slots removed
# baseline (speedup 1.0000x reference)
.LBB0_158:
	s_ashr_i32 s45, s44, 31
	s_lshl_b64 s[46:47], s[44:45], 19
	s_add_u32 s46, s90, s46
	s_addc_u32 s47, s91, s47
	s_and_b64 s[58:59], s[42:43], exec
	s_cselect_b32 s12, s47, s65
	s_cselect_b32 s45, s46, s64
	s_ashr_i32 s11, s10, 31
	s_lshl_b64 s[58:59], s[10:11], 19
	s_add_u32 s58, s14, s58
	s_addc_u32 s59, s15, s59
	s_and_b64 s[66:67], s[42:43], exec
	s_cselect_b32 s11, s59, s63
	s_cselect_b32 s73, s58, s62
	s_add_u32 s74, s62, 0x100
	s_addc_u32 s75, s63, 0
	s_add_u32 s62, s64, 0x40080
	s_addc_u32 s63, s65, 0
	s_mov_b32 s84, -2
	s_waitcnt lgkmcnt(0)
	s_add_u32 s3, s62, 0xfffc0080
	s_addc_u32 s64, s63, -1
	s_add_i32 s85, 0, 0x10000
	s_cmp_eq_u32 s84, 12
	s_cselect_b32 s67, s12, s64
	s_cselect_b32 s66, s45, s3
	v_add_u32_e32 v140, s85, v143
	s_cselect_b32 s65, s11, s75
	s_cselect_b32 s64, s73, s74
	s_add_i32 s3, 0, 0x14000
	ds_read_b128 v[152:155], v140
	ds_read_b128 v[156:159], v140 offset:1024
	ds_read_b128 v[160:163], v140 offset:2048
	ds_read_b128 v[164:167], v140 offset:3072
	v_add_u32_e32 v140, s3, v143
	ds_read_b128 v[168:171], v140
	ds_read_b128 v[172:175], v140 offset:1024
	ds_read_b128 v[176:179], v140 offset:2048
	ds_read_b128 v[180:183], v140 offset:3072
	s_add_i32 m0, s17, 0xc000
	ds_read_b128 v[184:187], v150
	ds_read_b128 v[188:191], v150 offset:1024
	ds_read_b128 v[192:195], v150 offset:2048
	ds_read_b128 v[226:229], v150 offset:3072
	ds_read_b128 v[230:233], v150 offset:4096
	ds_read_b128 v[234:237], v150 offset:5120
	ds_read_b128 v[238:241], v150 offset:6144
	ds_read_b128 v[242:245], v150 offset:7168
	global_load_lds_dwordx4 v138, s[62:63]
	s_add_i32 m0, s17, 0xe000
	s_nop 0
	global_load_lds_dwordx4 v136, s[62:63]
	s_waitcnt vmcnt(8)
	s_waitcnt lgkmcnt(0)
	s_barrier
	s_setprio 1
	s_waitcnt lgkmcnt(0)
	v_mfma_f32_16x16x32_bf16 v[122:125], v[152:155], v[184:187], 0
	v_mfma_f32_16x16x32_bf16 v[126:129], v[160:163], v[184:187], 0
	v_mfma_f32_16x16x32_bf16 v[106:109], v[152:155], v[192:195], 0
	v_mfma_f32_16x16x32_bf16 v[110:113], v[160:163], v[192:195], 0
	v_mfma_f32_16x16x32_bf16 v[90:93], v[152:155], v[230:233], 0
	v_mfma_f32_16x16x32_bf16 v[94:97], v[160:163], v[230:233], 0
	v_mfma_f32_16x16x32_bf16 v[74:77], v[152:155], v[238:241], 0
	v_mfma_f32_16x16x32_bf16 v[78:81], v[160:163], v[238:241], 0
	v_mfma_f32_16x16x32_bf16 v[122:125], v[156:159], v[188:191], v[122:125]
	v_mfma_f32_16x16x32_bf16 v[126:129], v[164:167], v[188:191], v[126:129]
	v_mfma_f32_16x16x32_bf16 v[106:109], v[156:159], v[226:229], v[106:109]
	v_mfma_f32_16x16x32_bf16 v[110:113], v[164:167], v[226:229], v[110:113]
	v_mfma_f32_16x16x32_bf16 v[90:93], v[156:159], v[234:237], v[90:93]
	v_mfma_f32_16x16x32_bf16 v[94:97], v[164:167], v[234:237], v[94:97]
	v_mfma_f32_16x16x32_bf16 v[74:77], v[156:159], v[242:245], v[74:77]
	v_mfma_f32_16x16x32_bf16 v[78:81], v[164:167], v[242:245], v[78:81]
	s_setprio 0
	s_setprio 1
	v_mfma_f32_16x16x32_bf16 v[114:117], v[168:171], v[184:187], 0
	v_mfma_f32_16x16x32_bf16 v[118:121], v[176:179], v[184:187], 0
	v_mfma_f32_16x16x32_bf16 v[98:101], v[168:171], v[192:195], 0
	v_mfma_f32_16x16x32_bf16 v[102:105], v[176:179], v[192:195], 0
	v_mfma_f32_16x16x32_bf16 v[82:85], v[168:171], v[230:233], 0
	v_mfma_f32_16x16x32_bf16 v[86:89], v[176:179], v[230:233], 0
	v_mfma_f32_16x16x32_bf16 v[66:69], v[168:171], v[238:241], 0
	v_mfma_f32_16x16x32_bf16 v[70:73], v[176:179], v[238:241], 0
	v_mfma_f32_16x16x32_bf16 v[114:117], v[172:175], v[188:191], v[114:117]
	v_mfma_f32_16x16x32_bf16 v[118:121], v[180:183], v[188:191], v[118:121]
	v_mfma_f32_16x16x32_bf16 v[98:101], v[172:175], v[226:229], v[98:101]
	v_mfma_f32_16x16x32_bf16 v[102:105], v[180:183], v[226:229], v[102:105]
	v_mfma_f32_16x16x32_bf16 v[82:85], v[172:175], v[234:237], v[82:85]
	v_mfma_f32_16x16x32_bf16 v[86:89], v[180:183], v[234:237], v[86:89]
	v_mfma_f32_16x16x32_bf16 v[66:69], v[172:175], v[242:245], v[66:69]
	v_mfma_f32_16x16x32_bf16 v[70:73], v[180:183], v[242:245], v[70:73]
	s_setprio 0
	s_barrier
	s_add_i32 s85, s85, s16
	v_lshl_add_u64 v[140:141], s[64:65], 0, v[144:145]
	s_mov_b32 m0, s85
	ds_read_b128 v[184:187], v150 offset:16384
	ds_read_b128 v[188:191], v150 offset:17408
	ds_read_b128 v[192:195], v150 offset:18432
	ds_read_b128 v[226:229], v150 offset:19456
	ds_read_b128 v[230:233], v150 offset:20480
	ds_read_b128 v[234:237], v150 offset:21504
	ds_read_b128 v[238:241], v150 offset:22528
	ds_read_b128 v[242:245], v150 offset:23552
	global_load_lds_dwordx4 v[140:141], off
	s_add_i32 m0, s85, 0x2000
	s_add_u32 s86, s64, 0x40000
	v_lshl_add_u64 v[196:197], s[64:65], 0, v[130:131]
	s_addc_u32 s87, s65, 0
	s_add_i32 s3, s3, s16
	global_load_lds_dwordx4 v[196:197], off
	s_mov_b32 m0, s3
	v_lshl_add_u64 v[210:211], s[66:67], 0, v[132:133]
	global_load_lds_dwordx4 v144, s[86:87]
	s_add_i32 m0, s3, 0x2000
	s_nop 0
	global_load_lds_dwordx4 v130, s[86:87]
	v_lshl_add_u64 v[206:207], s[66:67], 0, v[134:135]
	s_mov_b32 m0, s17
	s_nop 0
	global_load_lds_dwordx4 v[206:207], off
	s_mov_b32 m0, s18
	s_nop 0
	global_load_lds_dwordx4 v[210:211], off
	s_waitcnt vmcnt(8)
	s_waitcnt lgkmcnt(0)
	s_barrier
	s_setprio 1
	s_waitcnt lgkmcnt(0)
	v_mfma_f32_16x16x32_bf16 v[58:61], v[152:155], v[184:187], 0
	v_mfma_f32_16x16x32_bf16 v[62:65], v[160:163], v[184:187], 0
	v_mfma_f32_16x16x32_bf16 v[42:45], v[152:155], v[192:195], 0
	v_mfma_f32_16x16x32_bf16 v[46:49], v[160:163], v[192:195], 0
	v_mfma_f32_16x16x32_bf16 v[26:29], v[152:155], v[230:233], 0
	v_mfma_f32_16x16x32_bf16 v[30:33], v[160:163], v[230:233], 0
	v_mfma_f32_16x16x32_bf16 v[10:13], v[152:155], v[238:241], 0
	v_mfma_f32_16x16x32_bf16 v[14:17], v[160:163], v[238:241], 0
	v_mfma_f32_16x16x32_bf16 v[58:61], v[156:159], v[188:191], v[58:61]
	v_mfma_f32_16x16x32_bf16 v[62:65], v[164:167], v[188:191], v[62:65]
	v_mfma_f32_16x16x32_bf16 v[42:45], v[156:159], v[226:229], v[42:45]
	v_mfma_f32_16x16x32_bf16 v[46:49], v[164:167], v[226:229], v[46:49]
	v_mfma_f32_16x16x32_bf16 v[26:29], v[156:159], v[234:237], v[26:29]
	v_mfma_f32_16x16x32_bf16 v[30:33], v[164:167], v[234:237], v[30:33]
	v_mfma_f32_16x16x32_bf16 v[10:13], v[156:159], v[242:245], v[10:13]
	v_mfma_f32_16x16x32_bf16 v[14:17], v[164:167], v[242:245], v[14:17]
	s_setprio 0
	s_setprio 1
	v_mfma_f32_16x16x32_bf16 v[50:53], v[168:171], v[184:187], 0
	v_mfma_f32_16x16x32_bf16 v[54:57], v[176:179], v[184:187], 0
	v_mfma_f32_16x16x32_bf16 v[34:37], v[168:171], v[192:195], 0
	v_mfma_f32_16x16x32_bf16 v[38:41], v[176:179], v[192:195], 0
	v_mfma_f32_16x16x32_bf16 v[18:21], v[168:171], v[230:233], 0
	v_mfma_f32_16x16x32_bf16 v[22:25], v[176:179], v[230:233], 0
	v_mfma_f32_16x16x32_bf16 v[0:3], v[168:171], v[238:241], 0
	v_mfma_f32_16x16x32_bf16 v[4:7], v[176:179], v[238:241], 0
	v_mfma_f32_16x16x32_bf16 v[50:53], v[172:175], v[188:191], v[50:53]
	v_mfma_f32_16x16x32_bf16 v[54:57], v[180:183], v[188:191], v[54:57]
	v_mfma_f32_16x16x32_bf16 v[34:37], v[172:175], v[226:229], v[34:37]
	v_mfma_f32_16x16x32_bf16 v[38:41], v[180:183], v[226:229], v[38:41]
	v_mfma_f32_16x16x32_bf16 v[18:21], v[172:175], v[234:237], v[18:21]
	v_mfma_f32_16x16x32_bf16 v[22:25], v[180:183], v[234:237], v[22:25]
	v_mfma_f32_16x16x32_bf16 v[0:3], v[172:175], v[242:245], v[0:3]
	v_mfma_f32_16x16x32_bf16 v[4:7], v[180:183], v[242:245], v[4:7]
	s_setprio 0
	s_barrier
	s_branch .Lgemm_mid_0
.LBB0_159:
	s_add_u32 s3, s62, 0xfffc0080
	s_addc_u32 s64, s63, -1
	s_add_i32 s85, 0, 0x10000
	s_cmp_eq_u32 s84, 12
	s_cselect_b32 s67, s12, s64
	s_cselect_b32 s66, s45, s3
	v_add_u32_e32 v140, s85, v143
	s_cselect_b32 s65, s11, s75
	s_cselect_b32 s64, s73, s74
	s_add_i32 s3, 0, 0x14000
	ds_read_b128 v[152:155], v140
	ds_read_b128 v[156:159], v140 offset:1024
	ds_read_b128 v[160:163], v140 offset:2048
	ds_read_b128 v[164:167], v140 offset:3072
	v_add_u32_e32 v140, s3, v143
	ds_read_b128 v[168:171], v140
	ds_read_b128 v[172:175], v140 offset:1024
	ds_read_b128 v[176:179], v140 offset:2048
	ds_read_b128 v[180:183], v140 offset:3072
	s_add_i32 m0, s17, 0xc000
	ds_read_b128 v[184:187], v150
	ds_read_b128 v[188:191], v150 offset:1024
	ds_read_b128 v[192:195], v150 offset:2048
	ds_read_b128 v[226:229], v150 offset:3072
	ds_read_b128 v[230:233], v150 offset:4096
	ds_read_b128 v[234:237], v150 offset:5120
	ds_read_b128 v[238:241], v150 offset:6144
	ds_read_b128 v[242:245], v150 offset:7168
	global_load_lds_dwordx4 v138, s[62:63]
	s_add_i32 m0, s17, 0xe000
	s_nop 0
	global_load_lds_dwordx4 v136, s[62:63]
	s_waitcnt vmcnt(8)
	s_waitcnt lgkmcnt(0)
	s_barrier
	s_setprio 1
	s_waitcnt lgkmcnt(0)
	v_mfma_f32_16x16x32_bf16 v[122:125], v[152:155], v[184:187], v[122:125]
	v_mfma_f32_16x16x32_bf16 v[126:129], v[160:163], v[184:187], v[126:129]
	v_mfma_f32_16x16x32_bf16 v[106:109], v[152:155], v[192:195], v[106:109]
	v_mfma_f32_16x16x32_bf16 v[110:113], v[160:163], v[192:195], v[110:113]
	v_mfma_f32_16x16x32_bf16 v[90:93], v[152:155], v[230:233], v[90:93]
	v_mfma_f32_16x16x32_bf16 v[94:97], v[160:163], v[230:233], v[94:97]
	v_mfma_f32_16x16x32_bf16 v[74:77], v[152:155], v[238:241], v[74:77]
	v_mfma_f32_16x16x32_bf16 v[78:81], v[160:163], v[238:241], v[78:81]
	v_mfma_f32_16x16x32_bf16 v[122:125], v[156:159], v[188:191], v[122:125]
	v_mfma_f32_16x16x32_bf16 v[126:129], v[164:167], v[188:191], v[126:129]
	v_mfma_f32_16x16x32_bf16 v[106:109], v[156:159], v[226:229], v[106:109]
	v_mfma_f32_16x16x32_bf16 v[110:113], v[164:167], v[226:229], v[110:113]
	v_mfma_f32_16x16x32_bf16 v[90:93], v[156:159], v[234:237], v[90:93]
	v_mfma_f32_16x16x32_bf16 v[94:97], v[164:167], v[234:237], v[94:97]
	v_mfma_f32_16x16x32_bf16 v[74:77], v[156:159], v[242:245], v[74:77]
	v_mfma_f32_16x16x32_bf16 v[78:81], v[164:167], v[242:245], v[78:81]
	s_setprio 0
	s_setprio 1
	v_mfma_f32_16x16x32_bf16 v[114:117], v[168:171], v[184:187], v[114:117]
	v_mfma_f32_16x16x32_bf16 v[118:121], v[176:179], v[184:187], v[118:121]
	v_mfma_f32_16x16x32_bf16 v[98:101], v[168:171], v[192:195], v[98:101]
	v_mfma_f32_16x16x32_bf16 v[102:105], v[176:179], v[192:195], v[102:105]
	v_mfma_f32_16x16x32_bf16 v[82:85], v[168:171], v[230:233], v[82:85]
	v_mfma_f32_16x16x32_bf16 v[86:89], v[176:179], v[230:233], v[86:89]
	v_mfma_f32_16x16x32_bf16 v[66:69], v[168:171], v[238:241], v[66:69]
	v_mfma_f32_16x16x32_bf16 v[70:73], v[176:179], v[238:241], v[70:73]
	v_mfma_f32_16x16x32_bf16 v[114:117], v[172:175], v[188:191], v[114:117]
	v_mfma_f32_16x16x32_bf16 v[118:121], v[180:183], v[188:191], v[118:121]
	v_mfma_f32_16x16x32_bf16 v[98:101], v[172:175], v[226:229], v[98:101]
	v_mfma_f32_16x16x32_bf16 v[102:105], v[180:183], v[226:229], v[102:105]
	v_mfma_f32_16x16x32_bf16 v[82:85], v[172:175], v[234:237], v[82:85]
	v_mfma_f32_16x16x32_bf16 v[86:89], v[180:183], v[234:237], v[86:89]
	v_mfma_f32_16x16x32_bf16 v[66:69], v[172:175], v[242:245], v[66:69]
	v_mfma_f32_16x16x32_bf16 v[70:73], v[180:183], v[242:245], v[70:73]
	s_setprio 0
	s_barrier
	s_add_i32 s85, s85, s16
	v_lshl_add_u64 v[140:141], s[64:65], 0, v[144:145]
	s_mov_b32 m0, s85
	ds_read_b128 v[184:187], v150 offset:16384
	ds_read_b128 v[188:191], v150 offset:17408
	ds_read_b128 v[192:195], v150 offset:18432
	ds_read_b128 v[226:229], v150 offset:19456
	ds_read_b128 v[230:233], v150 offset:20480
	ds_read_b128 v[234:237], v150 offset:21504
	ds_read_b128 v[238:241], v150 offset:22528
	ds_read_b128 v[242:245], v150 offset:23552
	global_load_lds_dwordx4 v[140:141], off
	s_add_i32 m0, s85, 0x2000
	s_add_u32 s86, s64, 0x40000
	v_lshl_add_u64 v[196:197], s[64:65], 0, v[130:131]
	s_addc_u32 s87, s65, 0
	s_add_i32 s3, s3, s16
	global_load_lds_dwordx4 v[196:197], off
	s_mov_b32 m0, s3
	v_lshl_add_u64 v[210:211], s[66:67], 0, v[132:133]
	global_load_lds_dwordx4 v144, s[86:87]
	s_add_i32 m0, s3, 0x2000
	s_nop 0
	global_load_lds_dwordx4 v130, s[86:87]
	v_lshl_add_u64 v[206:207], s[66:67], 0, v[134:135]
	s_mov_b32 m0, s17
	s_nop 0
	global_load_lds_dwordx4 v[206:207], off
	s_mov_b32 m0, s18
	s_nop 0
	global_load_lds_dwordx4 v[210:211], off
	s_waitcnt vmcnt(8)
	s_waitcnt lgkmcnt(0)
	s_barrier
	s_setprio 1
	s_waitcnt lgkmcnt(0)
	v_mfma_f32_16x16x32_bf16 v[58:61], v[152:155], v[184:187], v[58:61]
	v_mfma_f32_16x16x32_bf16 v[62:65], v[160:163], v[184:187], v[62:65]
	v_mfma_f32_16x16x32_bf16 v[42:45], v[152:155], v[192:195], v[42:45]
	v_mfma_f32_16x16x32_bf16 v[46:49], v[160:163], v[192:195], v[46:49]
	v_mfma_f32_16x16x32_bf16 v[26:29], v[152:155], v[230:233], v[26:29]
	v_mfma_f32_16x16x32_bf16 v[30:33], v[160:163], v[230:233], v[30:33]
	v_mfma_f32_16x16x32_bf16 v[10:13], v[152:155], v[238:241], v[10:13]
	v_mfma_f32_16x16x32_bf16 v[14:17], v[160:163], v[238:241], v[14:17]
	v_mfma_f32_16x16x32_bf16 v[58:61], v[156:159], v[188:191], v[58:61]
	v_mfma_f32_16x16x32_bf16 v[62:65], v[164:167], v[188:191], v[62:65]
	v_mfma_f32_16x16x32_bf16 v[42:45], v[156:159], v[226:229], v[42:45]
	v_mfma_f32_16x16x32_bf16 v[46:49], v[164:167], v[226:229], v[46:49]
	v_mfma_f32_16x16x32_bf16 v[26:29], v[156:159], v[234:237], v[26:29]
	v_mfma_f32_16x16x32_bf16 v[30:33], v[164:167], v[234:237], v[30:33]
	v_mfma_f32_16x16x32_bf16 v[10:13], v[156:159], v[242:245], v[10:13]
	v_mfma_f32_16x16x32_bf16 v[14:17], v[164:167], v[242:245], v[14:17]
	s_setprio 0
	s_setprio 1
	v_mfma_f32_16x16x32_bf16 v[50:53], v[168:171], v[184:187], v[50:53]
	v_mfma_f32_16x16x32_bf16 v[54:57], v[176:179], v[184:187], v[54:57]
	v_mfma_f32_16x16x32_bf16 v[34:37], v[168:171], v[192:195], v[34:37]
	v_mfma_f32_16x16x32_bf16 v[38:41], v[176:179], v[192:195], v[38:41]
	v_mfma_f32_16x16x32_bf16 v[18:21], v[168:171], v[230:233], v[18:21]
	v_mfma_f32_16x16x32_bf16 v[22:25], v[176:179], v[230:233], v[22:25]
	v_mfma_f32_16x16x32_bf16 v[0:3], v[168:171], v[238:241], v[0:3]
	v_mfma_f32_16x16x32_bf16 v[4:7], v[176:179], v[238:241], v[4:7]
	v_mfma_f32_16x16x32_bf16 v[50:53], v[172:175], v[188:191], v[50:53]
	v_mfma_f32_16x16x32_bf16 v[54:57], v[180:183], v[188:191], v[54:57]
	v_mfma_f32_16x16x32_bf16 v[34:37], v[172:175], v[226:229], v[34:37]
	v_mfma_f32_16x16x32_bf16 v[38:41], v[180:183], v[226:229], v[38:41]
	v_mfma_f32_16x16x32_bf16 v[18:21], v[172:175], v[234:237], v[18:21]
	v_mfma_f32_16x16x32_bf16 v[22:25], v[180:183], v[234:237], v[22:25]
	v_mfma_f32_16x16x32_bf16 v[0:3], v[172:175], v[242:245], v[0:3]
	v_mfma_f32_16x16x32_bf16 v[4:7], v[180:183], v[242:245], v[4:7]
	s_setprio 0
	s_barrier
.Lgemm_mid_0:
	s_add_i32 s3, 0, 0x18000
	v_add_u32_e32 v151, s3, v143
	s_add_i32 s85, 0, 0x1c000
	ds_read_b128 v[152:155], v151
	ds_read_b128 v[156:159], v151 offset:1024
	ds_read_b128 v[160:163], v151 offset:2048
	ds_read_b128 v[164:167], v151 offset:3072
	v_add_u32_e32 v151, s85, v143
	ds_read_b128 v[168:171], v151
	ds_read_b128 v[172:175], v151 offset:1024
	ds_read_b128 v[176:179], v151 offset:2048
	ds_read_b128 v[180:183], v151 offset:3072
	s_add_u32 s66, s66, 0x40000
	s_addc_u32 s67, s67, 0
	s_mov_b32 m0, s20
	ds_read_b128 v[184:187], v150 offset:32768
	ds_read_b128 v[188:191], v150 offset:33792
	ds_read_b128 v[192:195], v150 offset:34816
	ds_read_b128 v[226:229], v150 offset:35840
	ds_read_b128 v[230:233], v150 offset:36864
	ds_read_b128 v[234:237], v150 offset:37888
	ds_read_b128 v[238:241], v150 offset:38912
	ds_read_b128 v[242:245], v150 offset:39936
	global_load_lds_dwordx4 v134, s[66:67]
	s_mov_b32 m0, s35
	s_nop 0
	global_load_lds_dwordx4 v132, s[66:67]
	s_waitcnt vmcnt(8)
	s_waitcnt lgkmcnt(0)
	s_barrier
	s_setprio 1
	s_waitcnt lgkmcnt(0)
	v_mfma_f32_16x16x32_bf16 v[122:125], v[152:155], v[184:187], v[122:125]
	v_mfma_f32_16x16x32_bf16 v[126:129], v[160:163], v[184:187], v[126:129]
	v_mfma_f32_16x16x32_bf16 v[106:109], v[152:155], v[192:195], v[106:109]
	v_mfma_f32_16x16x32_bf16 v[110:113], v[160:163], v[192:195], v[110:113]
	v_mfma_f32_16x16x32_bf16 v[90:93], v[152:155], v[230:233], v[90:93]
	v_mfma_f32_16x16x32_bf16 v[94:97], v[160:163], v[230:233], v[94:97]
	v_mfma_f32_16x16x32_bf16 v[74:77], v[152:155], v[238:241], v[74:77]
	v_mfma_f32_16x16x32_bf16 v[78:81], v[160:163], v[238:241], v[78:81]
	v_mfma_f32_16x16x32_bf16 v[122:125], v[156:159], v[188:191], v[122:125]
	v_mfma_f32_16x16x32_bf16 v[126:129], v[164:167], v[188:191], v[126:129]
	v_mfma_f32_16x16x32_bf16 v[106:109], v[156:159], v[226:229], v[106:109]
	v_mfma_f32_16x16x32_bf16 v[110:113], v[164:167], v[226:229], v[110:113]
	v_mfma_f32_16x16x32_bf16 v[90:93], v[156:159], v[234:237], v[90:93]
	v_mfma_f32_16x16x32_bf16 v[94:97], v[164:167], v[234:237], v[94:97]
	v_mfma_f32_16x16x32_bf16 v[74:77], v[156:159], v[242:245], v[74:77]
	v_mfma_f32_16x16x32_bf16 v[78:81], v[164:167], v[242:245], v[78:81]
	s_setprio 0
	s_setprio 1
	v_mfma_f32_16x16x32_bf16 v[114:117], v[168:171], v[184:187], v[114:117]
	v_mfma_f32_16x16x32_bf16 v[118:121], v[176:179], v[184:187], v[118:121]
	v_mfma_f32_16x16x32_bf16 v[98:101], v[168:171], v[192:195], v[98:101]
	v_mfma_f32_16x16x32_bf16 v[102:105], v[176:179], v[192:195], v[102:105]
	v_mfma_f32_16x16x32_bf16 v[82:85], v[168:171], v[230:233], v[82:85]
	v_mfma_f32_16x16x32_bf16 v[86:89], v[176:179], v[230:233], v[86:89]
	v_mfma_f32_16x16x32_bf16 v[66:69], v[168:171], v[238:241], v[66:69]
	v_mfma_f32_16x16x32_bf16 v[70:73], v[176:179], v[238:241], v[70:73]
	v_mfma_f32_16x16x32_bf16 v[114:117], v[172:175], v[188:191], v[114:117]
	v_mfma_f32_16x16x32_bf16 v[118:121], v[180:183], v[188:191], v[118:121]
	v_mfma_f32_16x16x32_bf16 v[98:101], v[172:175], v[226:229], v[98:101]
	v_mfma_f32_16x16x32_bf16 v[102:105], v[180:183], v[226:229], v[102:105]
	v_mfma_f32_16x16x32_bf16 v[82:85], v[172:175], v[234:237], v[82:85]
	v_mfma_f32_16x16x32_bf16 v[86:89], v[180:183], v[234:237], v[86:89]
	v_mfma_f32_16x16x32_bf16 v[66:69], v[172:175], v[242:245], v[66:69]
	v_mfma_f32_16x16x32_bf16 v[70:73], v[180:183], v[242:245], v[70:73]
	s_setprio 0
	s_barrier
	s_add_i32 s3, s3, s16
	v_lshl_add_u64 v[140:141], v[140:141], 0, s[96:97]
	s_mov_b32 m0, s3
	ds_read_b128 v[184:187], v150 offset:49152
	ds_read_b128 v[188:191], v150 offset:50176
	ds_read_b128 v[192:195], v150 offset:51200
	ds_read_b128 v[226:229], v150 offset:52224
	ds_read_b128 v[230:233], v150 offset:53248
	ds_read_b128 v[234:237], v150 offset:54272
	ds_read_b128 v[238:241], v150 offset:55296
	ds_read_b128 v[242:245], v150 offset:56320
	global_load_lds_dwordx4 v[140:141], off
	s_add_i32 m0, s3, 0x2000
	s_add_u32 s64, s64, 0x40080
	v_lshl_add_u64 v[140:141], v[196:197], 0, s[96:97]
	s_addc_u32 s65, s65, 0
	s_add_i32 s3, s85, s16
	global_load_lds_dwordx4 v[140:141], off
	s_mov_b32 m0, s3
	s_nop 0
	global_load_lds_dwordx4 v144, s[64:65]
	s_add_i32 m0, s3, 0x2000
	s_nop 0
	global_load_lds_dwordx4 v130, s[64:65]
	v_lshl_add_u64 v[140:141], v[206:207], 0, s[96:97]
	s_mov_b32 m0, s41
	s_nop 0
	global_load_lds_dwordx4 v[140:141], off
	v_lshl_add_u64 v[140:141], v[210:211], 0, s[96:97]
	s_mov_b32 m0, s68
	s_nop 0
	global_load_lds_dwordx4 v[140:141], off
	s_waitcnt vmcnt(8)
	s_waitcnt lgkmcnt(0)
	s_barrier
	s_setprio 1
	s_waitcnt lgkmcnt(0)
	v_mfma_f32_16x16x32_bf16 v[58:61], v[152:155], v[184:187], v[58:61]
	v_mfma_f32_16x16x32_bf16 v[62:65], v[160:163], v[184:187], v[62:65]
	v_mfma_f32_16x16x32_bf16 v[42:45], v[152:155], v[192:195], v[42:45]
	v_mfma_f32_16x16x32_bf16 v[46:49], v[160:163], v[192:195], v[46:49]
	v_mfma_f32_16x16x32_bf16 v[26:29], v[152:155], v[230:233], v[26:29]
	v_mfma_f32_16x16x32_bf16 v[30:33], v[160:163], v[230:233], v[30:33]
	v_mfma_f32_16x16x32_bf16 v[10:13], v[152:155], v[238:241], v[10:13]
	v_mfma_f32_16x16x32_bf16 v[14:17], v[160:163], v[238:241], v[14:17]
	v_mfma_f32_16x16x32_bf16 v[58:61], v[156:159], v[188:191], v[58:61]
	v_mfma_f32_16x16x32_bf16 v[62:65], v[164:167], v[188:191], v[62:65]
	v_mfma_f32_16x16x32_bf16 v[42:45], v[156:159], v[226:229], v[42:45]
	v_mfma_f32_16x16x32_bf16 v[46:49], v[164:167], v[226:229], v[46:49]
	v_mfma_f32_16x16x32_bf16 v[26:29], v[156:159], v[234:237], v[26:29]
	v_mfma_f32_16x16x32_bf16 v[30:33], v[164:167], v[234:237], v[30:33]
	v_mfma_f32_16x16x32_bf16 v[10:13], v[156:159], v[242:245], v[10:13]
	v_mfma_f32_16x16x32_bf16 v[14:17], v[164:167], v[242:245], v[14:17]
	s_setprio 0
	s_setprio 1
	v_mfma_f32_16x16x32_bf16 v[50:53], v[168:171], v[184:187], v[50:53]
	v_mfma_f32_16x16x32_bf16 v[54:57], v[176:179], v[184:187], v[54:57]
	v_mfma_f32_16x16x32_bf16 v[34:37], v[168:171], v[192:195], v[34:37]
	v_mfma_f32_16x16x32_bf16 v[38:41], v[176:179], v[192:195], v[38:41]
	v_mfma_f32_16x16x32_bf16 v[18:21], v[168:171], v[230:233], v[18:21]
	v_mfma_f32_16x16x32_bf16 v[22:25], v[176:179], v[230:233], v[22:25]
	v_mfma_f32_16x16x32_bf16 v[0:3], v[168:171], v[238:241], v[0:3]
	v_mfma_f32_16x16x32_bf16 v[4:7], v[176:179], v[238:241], v[4:7]
	v_mfma_f32_16x16x32_bf16 v[50:53], v[172:175], v[188:191], v[50:53]
	v_mfma_f32_16x16x32_bf16 v[54:57], v[180:183], v[188:191], v[54:57]
	v_mfma_f32_16x16x32_bf16 v[34:37], v[172:175], v[226:229], v[34:37]
	v_mfma_f32_16x16x32_bf16 v[38:41], v[180:183], v[226:229], v[38:41]
	v_mfma_f32_16x16x32_bf16 v[18:21], v[172:175], v[234:237], v[18:21]
	v_mfma_f32_16x16x32_bf16 v[22:25], v[180:183], v[234:237], v[22:25]
	v_mfma_f32_16x16x32_bf16 v[0:3], v[172:175], v[242:245], v[0:3]
	v_mfma_f32_16x16x32_bf16 v[4:7], v[180:183], v[242:245], v[4:7]
	s_setprio 0
	s_barrier
	s_add_i32 s84, s84, 2
	s_add_u32 s74, s74, 0x100
	s_addc_u32 s75, s75, 0
	s_add_u32 s62, s62, 0x100
	s_addc_u32 s63, s63, 0
	s_cmp_gt_u32 s84, 13
	s_cbranch_scc0 .LBB0_159
	s_and_b64 vcc, exec, s[8:9]
	s_cbranch_vccz .LBB0_162
	s_barrier

.LBB0_358:
	s_add_i32 vcc_hi, s3, 2
	s_add_u32 s50, s44, 0x80
	s_addc_u32 s51, s45, 0
	s_add_i32 s86, 0, 0x10000
	s_cmp_eq_u32 s12, s3
	s_cselect_b32 s61, s55, s51
	s_cselect_b32 s60, s54, s50
	v_add_u32_e32 v157, s86, v155
	s_cselect_b32 s51, s59, vcc_lo
	s_cselect_b32 s50, s58, s53
	s_add_i32 s3, 0, 0x14000
	ds_read_b128 v[140:143], v157
	ds_read_b128 v[150:153], v157 offset:1024
	ds_read_b128 v[158:161], v157 offset:2048
	ds_read_b128 v[162:165], v157 offset:3072
	v_add_u32_e32 v157, s3, v155
	ds_read_b128 v[166:169], v157
	ds_read_b128 v[170:173], v157 offset:1024
	ds_read_b128 v[174:177], v157 offset:2048
	ds_read_b128 v[178:181], v157 offset:3072
	s_add_i32 m0, s66, 0xc000
	ds_read_b128 v[182:185], v156
	ds_read_b128 v[186:189], v156 offset:1024
	ds_read_b128 v[190:193], v156 offset:2048
	ds_read_b128 v[194:197], v156 offset:3072
	ds_read_b128 v[226:229], v156 offset:4096
	ds_read_b128 v[230:233], v156 offset:5120
	ds_read_b128 v[234:237], v156 offset:6144
	ds_read_b128 v[238:241], v156 offset:7168
	global_load_lds_dwordx4 v138, s[44:45]
	s_add_i32 m0, s66, 0xe000
	s_nop 0
	global_load_lds_dwordx4 v136, s[44:45]
	s_waitcnt vmcnt(8)
	s_waitcnt lgkmcnt(0)
	s_barrier
	s_setprio 1
	s_waitcnt lgkmcnt(0)
	v_mfma_f32_16x16x32_bf16 v[126:129], v[140:143], v[182:185], v[126:129]
	v_mfma_f32_16x16x32_bf16 v[122:125], v[158:161], v[182:185], v[122:125]
	v_mfma_f32_16x16x32_bf16 v[110:113], v[140:143], v[190:193], v[110:113]
	v_mfma_f32_16x16x32_bf16 v[106:109], v[158:161], v[190:193], v[106:109]
	v_mfma_f32_16x16x32_bf16 v[94:97], v[140:143], v[226:229], v[94:97]
	v_mfma_f32_16x16x32_bf16 v[90:93], v[158:161], v[226:229], v[90:93]
	v_mfma_f32_16x16x32_bf16 v[78:81], v[140:143], v[234:237], v[78:81]
	v_mfma_f32_16x16x32_bf16 v[74:77], v[158:161], v[234:237], v[74:77]
	v_mfma_f32_16x16x32_bf16 v[126:129], v[150:153], v[186:189], v[126:129]
	v_mfma_f32_16x16x32_bf16 v[122:125], v[162:165], v[186:189], v[122:125]
	v_mfma_f32_16x16x32_bf16 v[110:113], v[150:153], v[194:197], v[110:113]
	v_mfma_f32_16x16x32_bf16 v[106:109], v[162:165], v[194:197], v[106:109]
	v_mfma_f32_16x16x32_bf16 v[94:97], v[150:153], v[230:233], v[94:97]
	v_mfma_f32_16x16x32_bf16 v[90:93], v[162:165], v[230:233], v[90:93]
	v_mfma_f32_16x16x32_bf16 v[78:81], v[150:153], v[238:241], v[78:81]
	v_mfma_f32_16x16x32_bf16 v[74:77], v[162:165], v[238:241], v[74:77]
	s_setprio 0
	s_setprio 1
	v_mfma_f32_16x16x32_bf16 v[118:121], v[166:169], v[182:185], v[118:121]
	v_mfma_f32_16x16x32_bf16 v[114:117], v[174:177], v[182:185], v[114:117]
	v_mfma_f32_16x16x32_bf16 v[102:105], v[166:169], v[190:193], v[102:105]
	v_mfma_f32_16x16x32_bf16 v[98:101], v[174:177], v[190:193], v[98:101]
	v_mfma_f32_16x16x32_bf16 v[86:89], v[166:169], v[226:229], v[86:89]
	v_mfma_f32_16x16x32_bf16 v[82:85], v[174:177], v[226:229], v[82:85]
	v_mfma_f32_16x16x32_bf16 v[70:73], v[166:169], v[234:237], v[70:73]
	v_mfma_f32_16x16x32_bf16 v[66:69], v[174:177], v[234:237], v[66:69]
	v_mfma_f32_16x16x32_bf16 v[118:121], v[170:173], v[186:189], v[118:121]
	v_mfma_f32_16x16x32_bf16 v[114:117], v[178:181], v[186:189], v[114:117]
	v_mfma_f32_16x16x32_bf16 v[102:105], v[170:173], v[194:197], v[102:105]
	v_mfma_f32_16x16x32_bf16 v[98:101], v[178:181], v[194:197], v[98:101]
	v_mfma_f32_16x16x32_bf16 v[86:89], v[170:173], v[230:233], v[86:89]
	v_mfma_f32_16x16x32_bf16 v[82:85], v[178:181], v[230:233], v[82:85]
	v_mfma_f32_16x16x32_bf16 v[70:73], v[170:173], v[238:241], v[70:73]
	v_mfma_f32_16x16x32_bf16 v[66:69], v[178:181], v[238:241], v[66:69]
	s_setprio 0
	s_barrier
	s_add_i32 s86, s86, s65
	v_lshl_add_u64 v[206:207], s[50:51], 0, v[144:145]
	s_mov_b32 m0, s86
	ds_read_b128 v[182:185], v156 offset:16384
	ds_read_b128 v[186:189], v156 offset:17408
	ds_read_b128 v[190:193], v156 offset:18432
	ds_read_b128 v[194:197], v156 offset:19456
	ds_read_b128 v[226:229], v156 offset:20480
	ds_read_b128 v[230:233], v156 offset:21504
	ds_read_b128 v[234:237], v156 offset:22528
	ds_read_b128 v[238:241], v156 offset:23552
	global_load_lds_dwordx4 v[206:207], off
	s_add_i32 m0, s86, 0x2000
	v_lshl_add_u64 v[242:243], s[50:51], 0, v[134:135]
	s_add_u32 s50, s50, s62
	s_addc_u32 s51, s51, 0
	s_add_i32 s3, s3, s65
	global_load_lds_dwordx4 v[242:243], off
	v_lshl_add_u64 v[244:245], s[50:51], 0, v[144:145]
	s_mov_b32 m0, s3
	v_lshl_add_u64 v[246:247], s[50:51], 0, v[134:135]
	global_load_lds_dwordx4 v[244:245], off
	s_add_i32 m0, s3, 0x2000
	v_lshl_add_u64 v[248:249], s[60:61], 0, v[130:131]
	global_load_lds_dwordx4 v[246:247], off
	s_mov_b32 m0, s66
	v_lshl_add_u64 v[250:251], s[60:61], 0, v[132:133]
	global_load_lds_dwordx4 v[248:249], off
	s_mov_b32 m0, s67
	s_nop 0
	global_load_lds_dwordx4 v[250:251], off
	s_waitcnt vmcnt(8)
	s_waitcnt lgkmcnt(0)
	s_barrier
	s_setprio 1
	s_waitcnt lgkmcnt(0)
	v_mfma_f32_16x16x32_bf16 v[62:65], v[140:143], v[182:185], v[62:65]
	v_mfma_f32_16x16x32_bf16 v[58:61], v[158:161], v[182:185], v[58:61]
	v_mfma_f32_16x16x32_bf16 v[46:49], v[140:143], v[190:193], v[46:49]
	v_mfma_f32_16x16x32_bf16 v[42:45], v[158:161], v[190:193], v[42:45]
	v_mfma_f32_16x16x32_bf16 v[30:33], v[140:143], v[226:229], v[30:33]
	v_mfma_f32_16x16x32_bf16 v[26:29], v[158:161], v[226:229], v[26:29]
	v_mfma_f32_16x16x32_bf16 v[14:17], v[140:143], v[234:237], v[14:17]
	v_mfma_f32_16x16x32_bf16 v[10:13], v[158:161], v[234:237], v[10:13]
	v_mfma_f32_16x16x32_bf16 v[62:65], v[150:153], v[186:189], v[62:65]
	v_mfma_f32_16x16x32_bf16 v[58:61], v[162:165], v[186:189], v[58:61]
	v_mfma_f32_16x16x32_bf16 v[46:49], v[150:153], v[194:197], v[46:49]
	v_mfma_f32_16x16x32_bf16 v[42:45], v[162:165], v[194:197], v[42:45]
	v_mfma_f32_16x16x32_bf16 v[30:33], v[150:153], v[230:233], v[30:33]
	v_mfma_f32_16x16x32_bf16 v[26:29], v[162:165], v[230:233], v[26:29]
	v_mfma_f32_16x16x32_bf16 v[14:17], v[150:153], v[238:241], v[14:17]
	v_mfma_f32_16x16x32_bf16 v[10:13], v[162:165], v[238:241], v[10:13]
	s_setprio 0
	s_setprio 1
	v_mfma_f32_16x16x32_bf16 v[54:57], v[166:169], v[182:185], v[54:57]
	v_mfma_f32_16x16x32_bf16 v[50:53], v[174:177], v[182:185], v[50:53]
	v_mfma_f32_16x16x32_bf16 v[38:41], v[166:169], v[190:193], v[38:41]
	v_mfma_f32_16x16x32_bf16 v[34:37], v[174:177], v[190:193], v[34:37]
	v_mfma_f32_16x16x32_bf16 v[22:25], v[166:169], v[226:229], v[22:25]
	v_mfma_f32_16x16x32_bf16 v[18:21], v[174:177], v[226:229], v[18:21]
	v_mfma_f32_16x16x32_bf16 v[4:7], v[166:169], v[234:237], v[4:7]
	v_mfma_f32_16x16x32_bf16 v[0:3], v[174:177], v[234:237], v[0:3]
	v_mfma_f32_16x16x32_bf16 v[54:57], v[170:173], v[186:189], v[54:57]
	v_mfma_f32_16x16x32_bf16 v[50:53], v[178:181], v[186:189], v[50:53]
	v_mfma_f32_16x16x32_bf16 v[38:41], v[170:173], v[194:197], v[38:41]
	v_mfma_f32_16x16x32_bf16 v[34:37], v[178:181], v[194:197], v[34:37]
	v_mfma_f32_16x16x32_bf16 v[22:25], v[170:173], v[230:233], v[22:25]
	v_mfma_f32_16x16x32_bf16 v[18:21], v[178:181], v[230:233], v[18:21]
	v_mfma_f32_16x16x32_bf16 v[4:7], v[170:173], v[238:241], v[4:7]
	v_mfma_f32_16x16x32_bf16 v[0:3], v[178:181], v[238:241], v[0:3]
	s_setprio 0
	s_barrier
	s_add_i32 s3, 0, 0x18000
	v_add_u32_e32 v157, s3, v155
	s_add_i32 s86, 0, 0x1c000
	ds_read_b128 v[140:143], v157
	ds_read_b128 v[150:153], v157 offset:1024
	ds_read_b128 v[158:161], v157 offset:2048
	ds_read_b128 v[162:165], v157 offset:3072
	v_add_u32_e32 v157, s86, v155
	ds_read_b128 v[166:169], v157
	ds_read_b128 v[170:173], v157 offset:1024
	ds_read_b128 v[174:177], v157 offset:2048
	ds_read_b128 v[178:181], v157 offset:3072
	s_add_u32 s50, s60, s38
	s_addc_u32 s51, s61, 0
	s_mov_b32 m0, s68
	ds_read_b128 v[182:185], v156 offset:32768
	ds_read_b128 v[186:189], v156 offset:33792
	ds_read_b128 v[190:193], v156 offset:34816
	ds_read_b128 v[194:197], v156 offset:35840
	ds_read_b128 v[226:229], v156 offset:36864
	ds_read_b128 v[230:233], v156 offset:37888
	ds_read_b128 v[234:237], v156 offset:38912
	ds_read_b128 v[238:241], v156 offset:39936
	global_load_lds_dwordx4 v130, s[50:51]
	s_mov_b32 m0, s69
	s_nop 0
	global_load_lds_dwordx4 v132, s[50:51]
	s_waitcnt vmcnt(8)
	s_waitcnt lgkmcnt(0)
	s_barrier
	s_setprio 1
	s_waitcnt lgkmcnt(0)
	v_mfma_f32_16x16x32_bf16 v[126:129], v[140:143], v[182:185], v[126:129]
	v_mfma_f32_16x16x32_bf16 v[122:125], v[158:161], v[182:185], v[122:125]
	v_mfma_f32_16x16x32_bf16 v[110:113], v[140:143], v[190:193], v[110:113]
	v_mfma_f32_16x16x32_bf16 v[106:109], v[158:161], v[190:193], v[106:109]
	v_mfma_f32_16x16x32_bf16 v[94:97], v[140:143], v[226:229], v[94:97]
	v_mfma_f32_16x16x32_bf16 v[90:93], v[158:161], v[226:229], v[90:93]
	v_mfma_f32_16x16x32_bf16 v[78:81], v[140:143], v[234:237], v[78:81]
	v_mfma_f32_16x16x32_bf16 v[74:77], v[158:161], v[234:237], v[74:77]
	v_mfma_f32_16x16x32_bf16 v[126:129], v[150:153], v[186:189], v[126:129]
	v_mfma_f32_16x16x32_bf16 v[122:125], v[162:165], v[186:189], v[122:125]
	v_mfma_f32_16x16x32_bf16 v[110:113], v[150:153], v[194:197], v[110:113]
	v_mfma_f32_16x16x32_bf16 v[106:109], v[162:165], v[194:197], v[106:109]
	v_mfma_f32_16x16x32_bf16 v[94:97], v[150:153], v[230:233], v[94:97]
	v_mfma_f32_16x16x32_bf16 v[90:93], v[162:165], v[230:233], v[90:93]
	v_mfma_f32_16x16x32_bf16 v[78:81], v[150:153], v[238:241], v[78:81]
	v_mfma_f32_16x16x32_bf16 v[74:77], v[162:165], v[238:241], v[74:77]
	s_setprio 0
	s_setprio 1
	v_mfma_f32_16x16x32_bf16 v[118:121], v[166:169], v[182:185], v[118:121]
	v_mfma_f32_16x16x32_bf16 v[114:117], v[174:177], v[182:185], v[114:117]
	v_mfma_f32_16x16x32_bf16 v[102:105], v[166:169], v[190:193], v[102:105]
	v_mfma_f32_16x16x32_bf16 v[98:101], v[174:177], v[190:193], v[98:101]
	v_mfma_f32_16x16x32_bf16 v[86:89], v[166:169], v[226:229], v[86:89]
	v_mfma_f32_16x16x32_bf16 v[82:85], v[174:177], v[226:229], v[82:85]
	v_mfma_f32_16x16x32_bf16 v[70:73], v[166:169], v[234:237], v[70:73]
	v_mfma_f32_16x16x32_bf16 v[66:69], v[174:177], v[234:237], v[66:69]
	v_mfma_f32_16x16x32_bf16 v[118:121], v[170:173], v[186:189], v[118:121]
	v_mfma_f32_16x16x32_bf16 v[114:117], v[178:181], v[186:189], v[114:117]
	v_mfma_f32_16x16x32_bf16 v[102:105], v[170:173], v[194:197], v[102:105]
	v_mfma_f32_16x16x32_bf16 v[98:101], v[178:181], v[194:197], v[98:101]
	v_mfma_f32_16x16x32_bf16 v[86:89], v[170:173], v[230:233], v[86:89]
	v_mfma_f32_16x16x32_bf16 v[82:85], v[178:181], v[230:233], v[82:85]
	v_mfma_f32_16x16x32_bf16 v[70:73], v[170:173], v[238:241], v[70:73]
	v_mfma_f32_16x16x32_bf16 v[66:69], v[178:181], v[238:241], v[66:69]
	s_setprio 0
	s_barrier
	s_add_i32 s3, s3, s65
	v_lshl_add_u64 v[206:207], v[206:207], 0, s[96:97]
	s_mov_b32 m0, s3
	ds_read_b128 v[182:185], v156 offset:49152
	ds_read_b128 v[186:189], v156 offset:50176
	ds_read_b128 v[190:193], v156 offset:51200
	ds_read_b128 v[194:197], v156 offset:52224
	ds_read_b128 v[226:229], v156 offset:53248
	ds_read_b128 v[230:233], v156 offset:54272
	ds_read_b128 v[234:237], v156 offset:55296
	ds_read_b128 v[238:241], v156 offset:56320
	global_load_lds_dwordx4 v[206:207], off
	v_lshl_add_u64 v[206:207], v[242:243], 0, s[96:97]
	s_add_i32 m0, s3, 0x2000
	s_add_i32 s3, s86, s65
	global_load_lds_dwordx4 v[206:207], off
	v_lshl_add_u64 v[206:207], v[244:245], 0, s[96:97]
	s_mov_b32 m0, s3
	s_nop 0
	global_load_lds_dwordx4 v[206:207], off
	v_lshl_add_u64 v[206:207], v[246:247], 0, s[96:97]
	s_add_i32 m0, s3, 0x2000
	s_nop 0
	global_load_lds_dwordx4 v[206:207], off
	v_lshl_add_u64 v[206:207], v[248:249], 0, s[96:97]
	s_mov_b32 m0, s71
	s_nop 0
	global_load_lds_dwordx4 v[206:207], off
	v_lshl_add_u64 v[206:207], v[250:251], 0, s[96:97]
	s_mov_b32 m0, s72
	s_nop 0
	global_load_lds_dwordx4 v[206:207], off
	s_waitcnt vmcnt(8)
	s_waitcnt lgkmcnt(0)
	s_barrier
	s_setprio 1
	s_waitcnt lgkmcnt(0)
	v_mfma_f32_16x16x32_bf16 v[62:65], v[140:143], v[182:185], v[62:65]
	v_mfma_f32_16x16x32_bf16 v[58:61], v[158:161], v[182:185], v[58:61]
	v_mfma_f32_16x16x32_bf16 v[46:49], v[140:143], v[190:193], v[46:49]
	v_mfma_f32_16x16x32_bf16 v[42:45], v[158:161], v[190:193], v[42:45]
	v_mfma_f32_16x16x32_bf16 v[30:33], v[140:143], v[226:229], v[30:33]
	v_mfma_f32_16x16x32_bf16 v[26:29], v[158:161], v[226:229], v[26:29]
	v_mfma_f32_16x16x32_bf16 v[14:17], v[140:143], v[234:237], v[14:17]
	v_mfma_f32_16x16x32_bf16 v[10:13], v[158:161], v[234:237], v[10:13]
	v_mfma_f32_16x16x32_bf16 v[62:65], v[150:153], v[186:189], v[62:65]
	v_mfma_f32_16x16x32_bf16 v[58:61], v[162:165], v[186:189], v[58:61]
	v_mfma_f32_16x16x32_bf16 v[46:49], v[150:153], v[194:197], v[46:49]
	v_mfma_f32_16x16x32_bf16 v[42:45], v[162:165], v[194:197], v[42:45]
	v_mfma_f32_16x16x32_bf16 v[30:33], v[150:153], v[230:233], v[30:33]
	v_mfma_f32_16x16x32_bf16 v[26:29], v[162:165], v[230:233], v[26:29]
	v_mfma_f32_16x16x32_bf16 v[14:17], v[150:153], v[238:241], v[14:17]
	v_mfma_f32_16x16x32_bf16 v[10:13], v[162:165], v[238:241], v[10:13]
	s_setprio 0
	s_setprio 1
	v_mfma_f32_16x16x32_bf16 v[54:57], v[166:169], v[182:185], v[54:57]
	v_mfma_f32_16x16x32_bf16 v[50:53], v[174:177], v[182:185], v[50:53]
	v_mfma_f32_16x16x32_bf16 v[38:41], v[166:169], v[190:193], v[38:41]
	v_mfma_f32_16x16x32_bf16 v[34:37], v[174:177], v[190:193], v[34:37]
	v_mfma_f32_16x16x32_bf16 v[22:25], v[166:169], v[226:229], v[22:25]
	v_mfma_f32_16x16x32_bf16 v[18:21], v[174:177], v[226:229], v[18:21]
	v_mfma_f32_16x16x32_bf16 v[4:7], v[166:169], v[234:237], v[4:7]
	v_mfma_f32_16x16x32_bf16 v[0:3], v[174:177], v[234:237], v[0:3]
	v_mfma_f32_16x16x32_bf16 v[54:57], v[170:173], v[186:189], v[54:57]
	v_mfma_f32_16x16x32_bf16 v[50:53], v[178:181], v[186:189], v[50:53]
	v_mfma_f32_16x16x32_bf16 v[38:41], v[170:173], v[194:197], v[38:41]
	v_mfma_f32_16x16x32_bf16 v[34:37], v[178:181], v[194:197], v[34:37]
	v_mfma_f32_16x16x32_bf16 v[22:25], v[170:173], v[230:233], v[22:25]
	v_mfma_f32_16x16x32_bf16 v[18:21], v[178:181], v[230:233], v[18:21]
	v_mfma_f32_16x16x32_bf16 v[4:7], v[170:173], v[238:241], v[4:7]
	v_mfma_f32_16x16x32_bf16 v[0:3], v[178:181], v[238:241], v[0:3]
	s_setprio 0
	s_barrier
	s_add_u32 s53, s53, 0x100
	s_addc_u32 vcc_lo, vcc_lo, 0
	s_add_u32 s44, s44, 0x100
	s_addc_u32 s45, s45, 0
	s_cmp_ge_i32 vcc_hi, s41
	s_mov_b32 s3, vcc_hi
	s_cbranch_scc0 .LBB0_358
	s_and_b64 vcc, exec, s[46:47]
	s_cbranch_vccz .LBB0_361

.LBB0_1181:
	v_max3_f32 v0, v96, v80, v97
	v_max3_f32 v1, v81, v98, v82
	s_cmp_eq_u32 s73, 0
	v_max3_f32 v0, v0, v99, v83
	v_max3_f32 v1, v1, v100, v84
	s_mov_b32 s3, 0xc2400000
	v_max3_f32 v0, v0, v101, v85
	v_max3_f32 v1, v1, v102, v86
	s_cselect_b64 s[42:43], -1, 0
	v_max3_f32 v0, v0, v103, v87
	v_max3_f32 v1, v1, v104, v88
	v_max3_f32 v0, v0, v105, v89
	v_max3_f32 v1, v1, v106, v90
	v_max3_f32 v0, v0, v107, v91
	v_max3_f32 v1, v1, v108, v92
	v_max3_f32 v0, v0, v109, v93
	v_max3_f32 v1, v1, v110, v94
	v_max3_f32 v0, v0, v1, v111
	v_max_f32_e32 v0, v0, v95
	v_mov_b32_e32 v1, v0
	s_nop 1
	v_permlane32_swap_b32_e32 v0, v1
	v_max_f32_e32 v0, v0, v1
	v_cmp_gt_f32_e64 s[44:45], s3, v0
	v_cmp_lt_f32_e32 vcc, s37, v0
	s_and_b64 s[44:45], s[42:43], s[44:45]
	s_or_b64 vcc, vcc, s[44:45]
	s_cbranch_vccz .LBB0_1183
	v_max_f32_e32 v1, v0, v0
	v_max_f32_e32 v1, 0, v1
	v_cndmask_b32_e64 v1, v1, v0, s[42:43]
	v_exp_f32_e64 v0, -v1
	v_add_f32_e32 v165, v165, v1
	v_sub_f32_e32 v111, v111, v1
	v_sub_f32_e32 v110, v110, v1
	v_cndmask_b32_e64 v0, v0, 1.0, s[42:43]
	v_pk_mul_f32 v[62:63], v[62:63], v[0:1] op_sel_hi:[1,0]
	v_pk_mul_f32 v[60:61], v[60:61], v[0:1] op_sel_hi:[1,0]
	v_pk_mul_f32 v[58:59], v[58:59], v[0:1] op_sel_hi:[1,0]
	v_pk_mul_f32 v[56:57], v[56:57], v[0:1] op_sel_hi:[1,0]
	v_pk_mul_f32 v[54:55], v[54:55], v[0:1] op_sel_hi:[1,0]
	v_pk_mul_f32 v[52:53], v[52:53], v[0:1] op_sel_hi:[1,0]
	v_pk_mul_f32 v[50:51], v[50:51], v[0:1] op_sel_hi:[1,0]
	v_pk_mul_f32 v[48:49], v[48:49], v[0:1] op_sel_hi:[1,0]
	v_pk_mul_f32 v[78:79], v[78:79], v[0:1] op_sel_hi:[1,0]
	v_pk_mul_f32 v[76:77], v[76:77], v[0:1] op_sel_hi:[1,0]
	v_pk_mul_f32 v[74:75], v[74:75], v[0:1] op_sel_hi:[1,0]
	v_pk_mul_f32 v[72:73], v[72:73], v[0:1] op_sel_hi:[1,0]
	v_pk_mul_f32 v[70:71], v[70:71], v[0:1] op_sel_hi:[1,0]
	v_pk_mul_f32 v[68:69], v[68:69], v[0:1] op_sel_hi:[1,0]
	v_pk_mul_f32 v[66:67], v[66:67], v[0:1] op_sel_hi:[1,0]
	v_pk_mul_f32 v[64:65], v[64:65], v[0:1] op_sel_hi:[1,0]
	v_pk_mul_f32 v[46:47], v[46:47], v[0:1] op_sel_hi:[1,0]
	v_pk_mul_f32 v[44:45], v[44:45], v[0:1] op_sel_hi:[1,0]
	v_pk_mul_f32 v[42:43], v[42:43], v[0:1] op_sel_hi:[1,0]
	v_pk_mul_f32 v[40:41], v[40:41], v[0:1] op_sel_hi:[1,0]
	v_pk_mul_f32 v[38:39], v[38:39], v[0:1] op_sel_hi:[1,0]
	v_pk_mul_f32 v[36:37], v[36:37], v[0:1] op_sel_hi:[1,0]
	v_pk_mul_f32 v[34:35], v[34:35], v[0:1] op_sel_hi:[1,0]
	v_pk_mul_f32 v[32:33], v[32:33], v[0:1] op_sel_hi:[1,0]
	v_pk_mul_f32 v[30:31], v[30:31], v[0:1] op_sel_hi:[1,0]
	v_pk_mul_f32 v[28:29], v[28:29], v[0:1] op_sel_hi:[1,0]
	v_pk_mul_f32 v[26:27], v[26:27], v[0:1] op_sel_hi:[1,0]
	v_pk_mul_f32 v[24:25], v[24:25], v[0:1] op_sel_hi:[1,0]
	v_pk_mul_f32 v[22:23], v[22:23], v[0:1] op_sel_hi:[1,0]
	v_pk_mul_f32 v[20:21], v[20:21], v[0:1] op_sel_hi:[1,0]
	v_pk_mul_f32 v[18:19], v[18:19], v[0:1] op_sel_hi:[1,0]
	v_pk_mul_f32 v[16:17], v[16:17], v[0:1] op_sel_hi:[1,0]
	v_sub_f32_e32 v109, v109, v1
	v_sub_f32_e32 v108, v108, v1
	v_sub_f32_e32 v107, v107, v1
	v_sub_f32_e32 v106, v106, v1
	v_sub_f32_e32 v105, v105, v1
	v_sub_f32_e32 v104, v104, v1
	v_sub_f32_e32 v103, v103, v1
	v_sub_f32_e32 v102, v102, v1
	v_sub_f32_e32 v101, v101, v1
	v_sub_f32_e32 v100, v100, v1
	v_sub_f32_e32 v99, v99, v1
	v_sub_f32_e32 v98, v98, v1
	v_sub_f32_e32 v97, v97, v1
	v_sub_f32_e32 v96, v96, v1
	v_sub_f32_e32 v95, v95, v1
	v_sub_f32_e32 v94, v94, v1
	v_sub_f32_e32 v93, v93, v1
	v_sub_f32_e32 v92, v92, v1
	v_sub_f32_e32 v91, v91, v1
	v_sub_f32_e32 v90, v90, v1
	v_sub_f32_e32 v89, v89, v1
	v_sub_f32_e32 v88, v88, v1
	v_sub_f32_e32 v87, v87, v1
	v_sub_f32_e32 v86, v86, v1
	v_sub_f32_e32 v85, v85, v1
	v_sub_f32_e32 v84, v84, v1
	v_sub_f32_e32 v83, v83, v1
	v_sub_f32_e32 v82, v82, v1
	v_sub_f32_e32 v81, v81, v1
	v_sub_f32_e32 v80, v80, v1
	v_mul_f32_e32 v161, v161, v0

.LBB0_1185:
	ds_read_b64_tr_b16 v[0:1], v166 offset:32768
	ds_read_b64_tr_b16 v[2:3], v158 offset:32768
	ds_read_b64_tr_b16 v[4:5], v167 offset:32768
	ds_read_b64_tr_b16 v[6:7], v160 offset:32768
	ds_read_b64_tr_b16 v[10:11], v168 offset:32768
	ds_read_b64_tr_b16 v[12:13], v162 offset:32768
	ds_read_b64_tr_b16 v[174:175], v169 offset:32768
	ds_read_b64_tr_b16 v[176:177], v163 offset:32768
	v_exp_f32_e32 v96, v96
	v_exp_f32_e32 v80, v80
	v_exp_f32_e32 v97, v97
	v_exp_f32_e32 v81, v81
	v_add_f32_e32 v9, 0, v96
	v_exp_f32_e32 v98, v98
	v_add_f32_e32 v9, v80, v9
	v_exp_f32_e32 v82, v82
	v_add_f32_e32 v9, v97, v9
	v_exp_f32_e32 v99, v99
	v_add_f32_e32 v9, v81, v9
	v_exp_f32_e32 v83, v83
	v_add_f32_e32 v9, v98, v9
	v_exp_f32_e32 v100, v100
	v_add_f32_e32 v9, v82, v9
	v_exp_f32_e32 v84, v84
	v_add_f32_e32 v9, v99, v9
	v_exp_f32_e32 v101, v101
	v_add_f32_e32 v9, v83, v9
	v_exp_f32_e32 v85, v85
	v_add_f32_e32 v9, v100, v9
	v_exp_f32_e32 v102, v102
	v_add_f32_e32 v9, v84, v9
	v_exp_f32_e32 v86, v86
	v_add_f32_e32 v9, v101, v9
	v_exp_f32_e32 v103, v103
	v_add_f32_e32 v9, v85, v9
	v_exp_f32_e32 v87, v87
	v_add_f32_e32 v9, v102, v9
	v_exp_f32_e32 v104, v104
	v_add_f32_e32 v9, v86, v9
	v_exp_f32_e32 v88, v88
	v_add_f32_e32 v9, v103, v9
	v_exp_f32_e32 v105, v105
	v_add_f32_e32 v9, v87, v9
	v_exp_f32_e32 v89, v89
	v_add_f32_e32 v9, v104, v9
	v_exp_f32_e32 v106, v106
	v_add_f32_e32 v9, v88, v9
	v_exp_f32_e32 v90, v90
	v_add_f32_e32 v9, v105, v9
	v_exp_f32_e32 v107, v107
	v_add_f32_e32 v9, v89, v9
	v_exp_f32_e32 v91, v91
	v_add_f32_e32 v9, v106, v9
	v_exp_f32_e32 v108, v108
	v_add_f32_e32 v9, v90, v9
	v_exp_f32_e32 v92, v92
	v_add_f32_e32 v9, v107, v9
	v_exp_f32_e32 v109, v109
	v_add_f32_e32 v9, v91, v9
	v_exp_f32_e32 v93, v93
	v_add_f32_e32 v9, v108, v9
	v_exp_f32_e32 v110, v110
	v_add_f32_e32 v9, v92, v9
	v_exp_f32_e32 v94, v94
	v_add_f32_e32 v9, v109, v9
	v_exp_f32_e32 v111, v111
	v_add_f32_e32 v9, v93, v9
	v_exp_f32_e32 v95, v95
	v_add_f32_e32 v9, v110, v9
	v_add_f32_e32 v9, v94, v9
	v_add_f32_e32 v9, v111, v9
	v_add_f32_e32 v9, v95, v9
	ds_read_b64_tr_b16 v[178:179], v166 offset:36864
	ds_read_b64_tr_b16 v[180:181], v158 offset:36864
	ds_read_b64_tr_b16 v[182:183], v167 offset:36864
	ds_read_b64_tr_b16 v[184:185], v160 offset:36864
	ds_read_b64_tr_b16 v[186:187], v168 offset:36864
	ds_read_b64_tr_b16 v[188:189], v162 offset:36864
	ds_read_b64_tr_b16 v[190:191], v169 offset:36864
	ds_read_b64_tr_b16 v[192:193], v163 offset:36864
	v_cvt_pk_bf16_f32 v194, v96, v97
	v_cvt_pk_bf16_f32 v195, v98, v99
	v_cvt_pk_bf16_f32 v196, v100, v101
	v_cvt_pk_bf16_f32 v197, v102, v103
	s_waitcnt lgkmcnt(14)
	s_nop 0
	v_mfma_f32_32x32x16_bf16 v[48:63], v[0:3], v[194:197], v[48:63]
	s_waitcnt lgkmcnt(12)
	v_mfma_f32_32x32x16_bf16 v[64:79], v[4:7], v[194:197], v[64:79]
	s_waitcnt lgkmcnt(10)
	v_mfma_f32_32x32x16_bf16 v[32:47], v[10:13], v[194:197], v[32:47]
	s_waitcnt lgkmcnt(8)
	v_mfma_f32_32x32x16_bf16 v[16:31], v[174:177], v[194:197], v[16:31]
	ds_read_b64_tr_b16 v[0:1], v166 offset:40960
	ds_read_b64_tr_b16 v[2:3], v158 offset:40960
	ds_read_b64_tr_b16 v[4:5], v167 offset:40960
	ds_read_b64_tr_b16 v[6:7], v160 offset:40960
	ds_read_b64_tr_b16 v[10:11], v168 offset:40960
	ds_read_b64_tr_b16 v[12:13], v162 offset:40960
	ds_read_b64_tr_b16 v[174:175], v169 offset:40960
	ds_read_b64_tr_b16 v[176:177], v163 offset:40960
	v_cvt_pk_bf16_f32 v194, v104, v105
	v_cvt_pk_bf16_f32 v195, v106, v107
	v_cvt_pk_bf16_f32 v196, v108, v109
	v_cvt_pk_bf16_f32 v197, v110, v111
	s_waitcnt lgkmcnt(14)
	s_nop 0
	v_mfma_f32_32x32x16_bf16 v[48:63], v[178:181], v[194:197], v[48:63]
	s_waitcnt lgkmcnt(12)
	v_mfma_f32_32x32x16_bf16 v[64:79], v[182:185], v[194:197], v[64:79]
	s_waitcnt lgkmcnt(10)
	v_mfma_f32_32x32x16_bf16 v[32:47], v[186:189], v[194:197], v[32:47]
	s_waitcnt lgkmcnt(8)
	v_mfma_f32_32x32x16_bf16 v[16:31], v[190:193], v[194:197], v[16:31]
	ds_read_b64_tr_b16 v[178:179], v166 offset:45056
	ds_read_b64_tr_b16 v[180:181], v158 offset:45056
	ds_read_b64_tr_b16 v[182:183], v167 offset:45056
	ds_read_b64_tr_b16 v[184:185], v160 offset:45056
	ds_read_b64_tr_b16 v[186:187], v168 offset:45056
	ds_read_b64_tr_b16 v[188:189], v162 offset:45056
	ds_read_b64_tr_b16 v[190:191], v169 offset:45056
	ds_read_b64_tr_b16 v[192:193], v163 offset:45056
	v_cvt_pk_bf16_f32 v194, v80, v81
	v_cvt_pk_bf16_f32 v195, v82, v83
	v_cvt_pk_bf16_f32 v196, v84, v85
	v_cvt_pk_bf16_f32 v197, v86, v87
	s_waitcnt lgkmcnt(14)
	s_nop 0
	v_mfma_f32_32x32x16_bf16 v[48:63], v[0:3], v[194:197], v[48:63]
	s_waitcnt lgkmcnt(12)
	v_mfma_f32_32x32x16_bf16 v[64:79], v[4:7], v[194:197], v[64:79]
	s_waitcnt lgkmcnt(10)
	v_mfma_f32_32x32x16_bf16 v[32:47], v[10:13], v[194:197], v[32:47]
	s_waitcnt lgkmcnt(8)
	v_mfma_f32_32x32x16_bf16 v[16:31], v[174:177], v[194:197], v[16:31]
	v_cvt_pk_bf16_f32 v0, v88, v89
	v_cvt_pk_bf16_f32 v1, v90, v91
	v_cvt_pk_bf16_f32 v2, v92, v93
	v_cvt_pk_bf16_f32 v3, v94, v95
	s_waitcnt vmcnt(0) lgkmcnt(0)
	s_barrier
	v_add_f32_e32 v161, v161, v9
	v_mfma_f32_32x32x16_bf16 v[48:63], v[178:181], v[0:3], v[48:63]
	s_and_b64 vcc, exec, s[42:43]
	v_mfma_f32_32x32x16_bf16 v[64:79], v[182:185], v[0:3], v[64:79]
	v_mfma_f32_32x32x16_bf16 v[32:47], v[186:189], v[0:3], v[32:47]
	v_mfma_f32_32x32x16_bf16 v[16:31], v[190:193], v[0:3], v[16:31]
	s_cbranch_vccnz .LBB0_1197
	s_add_i32 s3, s74, 3
	s_cmp_ge_u32 s3, s17
	s_cbranch_scc1 .LBB0_1199
	s_mov_b32 m0, s27
	s_nop 0
	global_load_lds_dwordx4 v150, s[62:63]
	s_add_i32 s3, s27, 0x400
	s_mov_b32 m0, s3
	s_nop 0
	global_load_lds_dwordx4 v144, s[62:63]
	s_andn2_b64 s[42:43], exec, s[68:69]
	s_andn2_b64 vcc, exec, s[68:69]
	s_cbranch_vccz .LBB0_1200

.LBB0_1192:
	v_max3_f32 v0, v128, v112, v129
	v_max3_f32 v1, v113, v130, v114
	v_max3_f32 v0, v0, v131, v115
	v_max3_f32 v1, v1, v132, v116
	v_max3_f32 v0, v0, v133, v117
	v_max3_f32 v1, v1, v134, v118
	v_max3_f32 v0, v0, v135, v119
	v_max3_f32 v1, v1, v136, v120
	v_max3_f32 v0, v0, v137, v121
	v_max3_f32 v1, v1, v138, v122
	v_max3_f32 v0, v0, v139, v123
	v_max3_f32 v1, v1, v140, v124
	v_max3_f32 v0, v0, v141, v125
	v_max3_f32 v1, v1, v142, v126
	v_max3_f32 v0, v0, v1, v143
	v_max_f32_e32 v0, v0, v127
	v_mov_b32_e32 v1, v0
	s_nop 1
	v_permlane32_swap_b32_e32 v0, v1
	v_max_f32_e32 v0, v0, v1
	v_cmp_lt_f32_e32 vcc, s37, v0
	s_cbranch_vccz .LBB0_1194
	v_max_f32_e32 v0, v0, v0
	v_max_f32_e32 v1, 0, v0
	v_exp_f32_e64 v0, -v1
	v_add_f32_e32 v165, v165, v1
	v_sub_f32_e32 v143, v143, v1
	v_sub_f32_e32 v142, v142, v1
	v_pk_mul_f32 v[62:63], v[62:63], v[0:1] op_sel_hi:[1,0]
	v_pk_mul_f32 v[60:61], v[60:61], v[0:1] op_sel_hi:[1,0]
	v_pk_mul_f32 v[58:59], v[58:59], v[0:1] op_sel_hi:[1,0]
	v_pk_mul_f32 v[56:57], v[56:57], v[0:1] op_sel_hi:[1,0]
	v_pk_mul_f32 v[54:55], v[54:55], v[0:1] op_sel_hi:[1,0]
	v_pk_mul_f32 v[52:53], v[52:53], v[0:1] op_sel_hi:[1,0]
	v_pk_mul_f32 v[50:51], v[50:51], v[0:1] op_sel_hi:[1,0]
	v_pk_mul_f32 v[48:49], v[48:49], v[0:1] op_sel_hi:[1,0]
	v_pk_mul_f32 v[78:79], v[78:79], v[0:1] op_sel_hi:[1,0]
	v_pk_mul_f32 v[76:77], v[76:77], v[0:1] op_sel_hi:[1,0]
	v_pk_mul_f32 v[74:75], v[74:75], v[0:1] op_sel_hi:[1,0]
	v_pk_mul_f32 v[72:73], v[72:73], v[0:1] op_sel_hi:[1,0]
	v_pk_mul_f32 v[70:71], v[70:71], v[0:1] op_sel_hi:[1,0]
	v_pk_mul_f32 v[68:69], v[68:69], v[0:1] op_sel_hi:[1,0]
	v_pk_mul_f32 v[66:67], v[66:67], v[0:1] op_sel_hi:[1,0]
	v_pk_mul_f32 v[64:65], v[64:65], v[0:1] op_sel_hi:[1,0]
	v_pk_mul_f32 v[46:47], v[46:47], v[0:1] op_sel_hi:[1,0]
	v_pk_mul_f32 v[44:45], v[44:45], v[0:1] op_sel_hi:[1,0]
	v_pk_mul_f32 v[42:43], v[42:43], v[0:1] op_sel_hi:[1,0]
	v_pk_mul_f32 v[40:41], v[40:41], v[0:1] op_sel_hi:[1,0]
	v_pk_mul_f32 v[38:39], v[38:39], v[0:1] op_sel_hi:[1,0]
	v_pk_mul_f32 v[36:37], v[36:37], v[0:1] op_sel_hi:[1,0]
	v_pk_mul_f32 v[34:35], v[34:35], v[0:1] op_sel_hi:[1,0]
	v_pk_mul_f32 v[32:33], v[32:33], v[0:1] op_sel_hi:[1,0]
	v_pk_mul_f32 v[30:31], v[30:31], v[0:1] op_sel_hi:[1,0]
	v_pk_mul_f32 v[28:29], v[28:29], v[0:1] op_sel_hi:[1,0]
	v_pk_mul_f32 v[26:27], v[26:27], v[0:1] op_sel_hi:[1,0]
	v_pk_mul_f32 v[24:25], v[24:25], v[0:1] op_sel_hi:[1,0]
	v_pk_mul_f32 v[22:23], v[22:23], v[0:1] op_sel_hi:[1,0]
	v_pk_mul_f32 v[20:21], v[20:21], v[0:1] op_sel_hi:[1,0]
	v_pk_mul_f32 v[18:19], v[18:19], v[0:1] op_sel_hi:[1,0]
	v_pk_mul_f32 v[16:17], v[16:17], v[0:1] op_sel_hi:[1,0]
	v_sub_f32_e32 v141, v141, v1
	v_sub_f32_e32 v140, v140, v1
	v_sub_f32_e32 v139, v139, v1
	v_sub_f32_e32 v138, v138, v1
	v_sub_f32_e32 v137, v137, v1
	v_sub_f32_e32 v136, v136, v1
	v_sub_f32_e32 v135, v135, v1
	v_sub_f32_e32 v134, v134, v1
	v_sub_f32_e32 v133, v133, v1
	v_sub_f32_e32 v132, v132, v1
	v_sub_f32_e32 v131, v131, v1
	v_sub_f32_e32 v130, v130, v1
	v_sub_f32_e32 v129, v129, v1
	v_sub_f32_e32 v128, v128, v1
	v_sub_f32_e32 v127, v127, v1
	v_sub_f32_e32 v126, v126, v1
	v_sub_f32_e32 v125, v125, v1
	v_sub_f32_e32 v124, v124, v1
	v_sub_f32_e32 v123, v123, v1
	v_sub_f32_e32 v122, v122, v1
	v_sub_f32_e32 v121, v121, v1
	v_sub_f32_e32 v120, v120, v1
	v_sub_f32_e32 v119, v119, v1
	v_sub_f32_e32 v118, v118, v1
	v_sub_f32_e32 v117, v117, v1
	v_sub_f32_e32 v116, v116, v1
	v_sub_f32_e32 v115, v115, v1
	v_sub_f32_e32 v114, v114, v1
	v_sub_f32_e32 v113, v113, v1
	v_sub_f32_e32 v112, v112, v1
	v_mul_f32_e32 v161, v161, v0

.LBB0_1196:
	ds_read_b64_tr_b16 v[0:1], v166 offset:49152
	ds_read_b64_tr_b16 v[2:3], v158 offset:49152
	ds_read_b64_tr_b16 v[4:5], v167 offset:49152
	ds_read_b64_tr_b16 v[6:7], v160 offset:49152
	ds_read_b64_tr_b16 v[10:11], v168 offset:49152
	ds_read_b64_tr_b16 v[12:13], v162 offset:49152
	ds_read_b64_tr_b16 v[174:175], v169 offset:49152
	ds_read_b64_tr_b16 v[176:177], v163 offset:49152
	v_exp_f32_e32 v128, v128
	v_exp_f32_e32 v112, v112
	v_exp_f32_e32 v129, v129
	v_exp_f32_e32 v113, v113
	v_add_f32_e32 v9, 0, v128
	v_exp_f32_e32 v130, v130
	v_add_f32_e32 v9, v112, v9
	v_exp_f32_e32 v114, v114
	v_add_f32_e32 v9, v129, v9
	v_exp_f32_e32 v131, v131
	v_add_f32_e32 v9, v113, v9
	v_exp_f32_e32 v115, v115
	v_add_f32_e32 v9, v130, v9
	v_exp_f32_e32 v132, v132
	v_add_f32_e32 v9, v114, v9
	v_exp_f32_e32 v116, v116
	v_add_f32_e32 v9, v131, v9
	v_exp_f32_e32 v133, v133
	v_add_f32_e32 v9, v115, v9
	v_exp_f32_e32 v117, v117
	v_add_f32_e32 v9, v132, v9
	v_exp_f32_e32 v134, v134
	v_add_f32_e32 v9, v116, v9
	v_exp_f32_e32 v118, v118
	v_add_f32_e32 v9, v133, v9
	v_exp_f32_e32 v135, v135
	v_add_f32_e32 v9, v117, v9
	v_exp_f32_e32 v119, v119
	v_add_f32_e32 v9, v134, v9
	v_exp_f32_e32 v136, v136
	v_add_f32_e32 v9, v118, v9
	v_exp_f32_e32 v120, v120
	v_add_f32_e32 v9, v135, v9
	v_exp_f32_e32 v137, v137
	v_add_f32_e32 v9, v119, v9
	v_exp_f32_e32 v121, v121
	v_add_f32_e32 v9, v136, v9
	v_exp_f32_e32 v138, v138
	v_add_f32_e32 v9, v120, v9
	v_exp_f32_e32 v122, v122
	v_add_f32_e32 v9, v137, v9
	v_exp_f32_e32 v139, v139
	v_add_f32_e32 v9, v121, v9
	v_exp_f32_e32 v123, v123
	v_add_f32_e32 v9, v138, v9
	v_exp_f32_e32 v140, v140
	v_add_f32_e32 v9, v122, v9
	v_exp_f32_e32 v124, v124
	v_add_f32_e32 v9, v139, v9
	v_exp_f32_e32 v141, v141
	v_add_f32_e32 v9, v123, v9
	v_exp_f32_e32 v125, v125
	v_add_f32_e32 v9, v140, v9
	v_exp_f32_e32 v142, v142
	v_add_f32_e32 v9, v124, v9
	v_exp_f32_e32 v126, v126
	v_add_f32_e32 v9, v141, v9
	v_exp_f32_e32 v143, v143
	v_add_f32_e32 v9, v125, v9
	v_exp_f32_e32 v127, v127
	v_add_f32_e32 v9, v142, v9
	v_add_f32_e32 v9, v126, v9
	v_add_f32_e32 v9, v143, v9
	v_add_f32_e32 v9, v127, v9
	ds_read_b64_tr_b16 v[178:179], v166 offset:53248
	ds_read_b64_tr_b16 v[180:181], v158 offset:53248
	ds_read_b64_tr_b16 v[182:183], v167 offset:53248
	ds_read_b64_tr_b16 v[184:185], v160 offset:53248
	ds_read_b64_tr_b16 v[186:187], v168 offset:53248
	ds_read_b64_tr_b16 v[188:189], v162 offset:53248
	ds_read_b64_tr_b16 v[190:191], v169 offset:53248
	ds_read_b64_tr_b16 v[192:193], v163 offset:53248
	v_cvt_pk_bf16_f32 v194, v128, v129
	v_cvt_pk_bf16_f32 v195, v130, v131
	v_cvt_pk_bf16_f32 v196, v132, v133
	v_cvt_pk_bf16_f32 v197, v134, v135
	s_waitcnt lgkmcnt(14)
	s_nop 0
	v_mfma_f32_32x32x16_bf16 v[48:63], v[0:3], v[194:197], v[48:63]
	s_waitcnt lgkmcnt(12)
	v_mfma_f32_32x32x16_bf16 v[64:79], v[4:7], v[194:197], v[64:79]
	s_waitcnt lgkmcnt(10)
	v_mfma_f32_32x32x16_bf16 v[32:47], v[10:13], v[194:197], v[32:47]
	s_waitcnt lgkmcnt(8)
	v_mfma_f32_32x32x16_bf16 v[16:31], v[174:177], v[194:197], v[16:31]
	ds_read_b64_tr_b16 v[0:1], v166 offset:57344
	ds_read_b64_tr_b16 v[2:3], v158 offset:57344
	ds_read_b64_tr_b16 v[4:5], v167 offset:57344
	ds_read_b64_tr_b16 v[6:7], v160 offset:57344
	ds_read_b64_tr_b16 v[10:11], v168 offset:57344
	ds_read_b64_tr_b16 v[12:13], v162 offset:57344
	ds_read_b64_tr_b16 v[174:175], v169 offset:57344
	ds_read_b64_tr_b16 v[176:177], v163 offset:57344
	v_cvt_pk_bf16_f32 v194, v136, v137
	v_cvt_pk_bf16_f32 v195, v138, v139
	v_cvt_pk_bf16_f32 v196, v140, v141
	v_cvt_pk_bf16_f32 v197, v142, v143
	s_waitcnt lgkmcnt(14)
	s_nop 0
	v_mfma_f32_32x32x16_bf16 v[48:63], v[178:181], v[194:197], v[48:63]
	s_waitcnt lgkmcnt(12)
	v_mfma_f32_32x32x16_bf16 v[64:79], v[182:185], v[194:197], v[64:79]
	s_waitcnt lgkmcnt(10)
	v_mfma_f32_32x32x16_bf16 v[32:47], v[186:189], v[194:197], v[32:47]
	s_waitcnt lgkmcnt(8)
	v_mfma_f32_32x32x16_bf16 v[16:31], v[190:193], v[194:197], v[16:31]
	ds_read_b64_tr_b16 v[178:179], v166 offset:61440
	ds_read_b64_tr_b16 v[180:181], v158 offset:61440
	ds_read_b64_tr_b16 v[182:183], v167 offset:61440
	ds_read_b64_tr_b16 v[184:185], v160 offset:61440
	ds_read_b64_tr_b16 v[186:187], v168 offset:61440
	ds_read_b64_tr_b16 v[188:189], v162 offset:61440
	ds_read_b64_tr_b16 v[170:171], v169 offset:61440
	ds_read_b64_tr_b16 v[172:173], v163 offset:61440
	v_cvt_pk_bf16_f32 v190, v112, v113
	v_cvt_pk_bf16_f32 v191, v114, v115
	v_cvt_pk_bf16_f32 v192, v116, v117
	v_cvt_pk_bf16_f32 v193, v118, v119
	s_waitcnt lgkmcnt(14)
	s_nop 0
	v_mfma_f32_32x32x16_bf16 v[48:63], v[0:3], v[190:193], v[48:63]
	s_waitcnt lgkmcnt(12)
	v_mfma_f32_32x32x16_bf16 v[64:79], v[4:7], v[190:193], v[64:79]
	s_waitcnt lgkmcnt(10)
	v_mfma_f32_32x32x16_bf16 v[32:47], v[10:13], v[190:193], v[32:47]
	s_waitcnt lgkmcnt(8)
	v_mfma_f32_32x32x16_bf16 v[16:31], v[174:177], v[190:193], v[16:31]
	v_cvt_pk_bf16_f32 v0, v120, v121
	v_cvt_pk_bf16_f32 v1, v122, v123
	v_cvt_pk_bf16_f32 v2, v124, v125
	v_cvt_pk_bf16_f32 v3, v126, v127
	s_waitcnt vmcnt(0) lgkmcnt(0)
	s_barrier
	v_add_f32_e32 v161, v161, v9
	v_mfma_f32_32x32x16_bf16 v[48:63], v[178:181], v[0:3], v[48:63]
	v_mfma_f32_32x32x16_bf16 v[64:79], v[182:185], v[0:3], v[64:79]
	v_mfma_f32_32x32x16_bf16 v[32:47], v[186:189], v[0:3], v[32:47]
	v_mfma_f32_32x32x16_bf16 v[16:31], v[170:173], v[0:3], v[16:31]

.LBB0_1240:
	s_ashr_i32 s11, s10, 31
	s_lshl_b64 s[44:45], s[10:11], 19
	s_add_u32 s44, s90, s44
	s_addc_u32 s45, s91, s45
	s_and_b64 s[46:47], s[40:41], exec
	s_cselect_b32 s11, s45, s53
	s_cselect_b32 s12, s44, s52
	s_ashr_i32 s9, s8, 31
	s_lshl_b64 s[46:47], s[8:9], 19
	s_add_u32 s46, s14, s46
	s_addc_u32 s47, s15, s47
	s_and_b64 s[54:55], s[40:41], exec
	s_cselect_b32 s9, s47, s51
	s_cselect_b32 s38, s46, s50
	s_add_u32 s43, s50, 0x100
	s_addc_u32 s49, s51, 0
	s_add_u32 s50, s52, 0x40080
	s_addc_u32 s51, s53, 0
	s_mov_b32 s58, -2
	s_waitcnt lgkmcnt(0)
	s_add_u32 s3, s50, 0xfffc0080
	s_addc_u32 s52, s51, -1
	s_add_i32 s59, 0, 0x10000
	s_cmp_eq_u32 s58, 12
	s_cselect_b32 s55, s11, s52
	s_cselect_b32 s54, s12, s3
	v_add_u32_e32 v142, s59, v153
	s_cselect_b32 s53, s9, s49
	s_cselect_b32 s52, s38, s43
	s_add_i32 s3, 0, 0x14000
	ds_read_b128 v[156:159], v142
	ds_read_b128 v[160:163], v142 offset:1024
	ds_read_b128 v[164:167], v142 offset:2048
	ds_read_b128 v[168:171], v142 offset:3072
	v_add_u32_e32 v142, s3, v153
	ds_read_b128 v[172:175], v142
	ds_read_b128 v[176:179], v142 offset:1024
	ds_read_b128 v[180:183], v142 offset:2048
	ds_read_b128 v[184:187], v142 offset:3072
	s_add_i32 m0, s17, 0xc000
	ds_read_b128 v[188:191], v154
	ds_read_b128 v[192:195], v154 offset:1024
	ds_read_b128 v[226:229], v154 offset:2048
	ds_read_b128 v[230:233], v154 offset:3072
	ds_read_b128 v[234:237], v154 offset:4096
	ds_read_b128 v[238:241], v154 offset:5120
	ds_read_b128 v[242:245], v154 offset:6144
	ds_read_b128 v[246:249], v154 offset:7168
	global_load_lds_dwordx4 v140, s[50:51]
	s_add_i32 m0, s17, 0xe000
	s_nop 0
	global_load_lds_dwordx4 v138, s[50:51]
	s_waitcnt vmcnt(8)
	s_waitcnt lgkmcnt(0)
	s_barrier
	s_setprio 1
	s_waitcnt lgkmcnt(0)
	v_mfma_f32_16x16x32_bf16 v[126:129], v[156:159], v[188:191], 0
	v_mfma_f32_16x16x32_bf16 v[122:125], v[164:167], v[188:191], 0
	v_mfma_f32_16x16x32_bf16 v[110:113], v[156:159], v[226:229], 0
	v_mfma_f32_16x16x32_bf16 v[106:109], v[164:167], v[226:229], 0
	v_mfma_f32_16x16x32_bf16 v[94:97], v[156:159], v[234:237], 0
	v_mfma_f32_16x16x32_bf16 v[90:93], v[164:167], v[234:237], 0
	v_mfma_f32_16x16x32_bf16 v[78:81], v[156:159], v[242:245], 0
	v_mfma_f32_16x16x32_bf16 v[74:77], v[164:167], v[242:245], 0
	v_mfma_f32_16x16x32_bf16 v[126:129], v[160:163], v[192:195], v[126:129]
	v_mfma_f32_16x16x32_bf16 v[122:125], v[168:171], v[192:195], v[122:125]
	v_mfma_f32_16x16x32_bf16 v[110:113], v[160:163], v[230:233], v[110:113]
	v_mfma_f32_16x16x32_bf16 v[106:109], v[168:171], v[230:233], v[106:109]
	v_mfma_f32_16x16x32_bf16 v[94:97], v[160:163], v[238:241], v[94:97]
	v_mfma_f32_16x16x32_bf16 v[90:93], v[168:171], v[238:241], v[90:93]
	v_mfma_f32_16x16x32_bf16 v[78:81], v[160:163], v[246:249], v[78:81]
	v_mfma_f32_16x16x32_bf16 v[74:77], v[168:171], v[246:249], v[74:77]
	s_setprio 0
	s_setprio 1
	v_mfma_f32_16x16x32_bf16 v[118:121], v[172:175], v[188:191], 0
	v_mfma_f32_16x16x32_bf16 v[114:117], v[180:183], v[188:191], 0
	v_mfma_f32_16x16x32_bf16 v[102:105], v[172:175], v[226:229], 0
	v_mfma_f32_16x16x32_bf16 v[98:101], v[180:183], v[226:229], 0
	v_mfma_f32_16x16x32_bf16 v[86:89], v[172:175], v[234:237], 0
	v_mfma_f32_16x16x32_bf16 v[82:85], v[180:183], v[234:237], 0
	v_mfma_f32_16x16x32_bf16 v[70:73], v[172:175], v[242:245], 0
	v_mfma_f32_16x16x32_bf16 v[66:69], v[180:183], v[242:245], 0
	v_mfma_f32_16x16x32_bf16 v[118:121], v[176:179], v[192:195], v[118:121]
	v_mfma_f32_16x16x32_bf16 v[114:117], v[184:187], v[192:195], v[114:117]
	v_mfma_f32_16x16x32_bf16 v[102:105], v[176:179], v[230:233], v[102:105]
	v_mfma_f32_16x16x32_bf16 v[98:101], v[184:187], v[230:233], v[98:101]
	v_mfma_f32_16x16x32_bf16 v[86:89], v[176:179], v[238:241], v[86:89]
	v_mfma_f32_16x16x32_bf16 v[82:85], v[184:187], v[238:241], v[82:85]
	v_mfma_f32_16x16x32_bf16 v[70:73], v[176:179], v[246:249], v[70:73]
	v_mfma_f32_16x16x32_bf16 v[66:69], v[184:187], v[246:249], v[66:69]
	s_setprio 0
	s_barrier
	s_add_i32 s59, s59, s16
	v_lshl_add_u64 v[142:143], s[52:53], 0, v[132:133]
	s_mov_b32 m0, s59
	ds_read_b128 v[188:191], v154 offset:16384
	ds_read_b128 v[192:195], v154 offset:17408
	ds_read_b128 v[226:229], v154 offset:18432
	ds_read_b128 v[230:233], v154 offset:19456
	ds_read_b128 v[234:237], v154 offset:20480
	ds_read_b128 v[238:241], v154 offset:21504
	ds_read_b128 v[242:245], v154 offset:22528
	ds_read_b128 v[246:249], v154 offset:23552
	global_load_lds_dwordx4 v[142:143], off
	s_add_i32 m0, s59, 0x2000
	s_add_u32 s60, s52, 0x40000
	v_lshl_add_u64 v[150:151], s[52:53], 0, v[136:137]
	s_addc_u32 s61, s53, 0
	s_add_i32 s3, s3, s16
	global_load_lds_dwordx4 v[150:151], off
	s_mov_b32 m0, s3
	v_lshl_add_u64 v[250:251], s[54:55], 0, v[134:135]
	global_load_lds_dwordx4 v132, s[60:61]
	s_add_i32 m0, s3, 0x2000
	s_nop 0
	global_load_lds_dwordx4 v136, s[60:61]
	v_lshl_add_u64 v[196:197], s[54:55], 0, v[130:131]
	s_mov_b32 m0, s17
	s_nop 0
	global_load_lds_dwordx4 v[196:197], off
	s_mov_b32 m0, s18
	s_nop 0
	global_load_lds_dwordx4 v[250:251], off
	s_waitcnt vmcnt(8)
	s_waitcnt lgkmcnt(0)
	s_barrier
	s_setprio 1
	s_waitcnt lgkmcnt(0)
	v_mfma_f32_16x16x32_bf16 v[62:65], v[156:159], v[188:191], 0
	v_mfma_f32_16x16x32_bf16 v[58:61], v[164:167], v[188:191], 0
	v_mfma_f32_16x16x32_bf16 v[46:49], v[156:159], v[226:229], 0
	v_mfma_f32_16x16x32_bf16 v[42:45], v[164:167], v[226:229], 0
	v_mfma_f32_16x16x32_bf16 v[30:33], v[156:159], v[234:237], 0
	v_mfma_f32_16x16x32_bf16 v[26:29], v[164:167], v[234:237], 0
	v_mfma_f32_16x16x32_bf16 v[14:17], v[156:159], v[242:245], 0
	v_mfma_f32_16x16x32_bf16 v[10:13], v[164:167], v[242:245], 0
	v_mfma_f32_16x16x32_bf16 v[62:65], v[160:163], v[192:195], v[62:65]
	v_mfma_f32_16x16x32_bf16 v[58:61], v[168:171], v[192:195], v[58:61]
	v_mfma_f32_16x16x32_bf16 v[46:49], v[160:163], v[230:233], v[46:49]
	v_mfma_f32_16x16x32_bf16 v[42:45], v[168:171], v[230:233], v[42:45]
	v_mfma_f32_16x16x32_bf16 v[30:33], v[160:163], v[238:241], v[30:33]
	v_mfma_f32_16x16x32_bf16 v[26:29], v[168:171], v[238:241], v[26:29]
	v_mfma_f32_16x16x32_bf16 v[14:17], v[160:163], v[246:249], v[14:17]
	v_mfma_f32_16x16x32_bf16 v[10:13], v[168:171], v[246:249], v[10:13]
	s_setprio 0
	s_setprio 1
	v_mfma_f32_16x16x32_bf16 v[54:57], v[172:175], v[188:191], 0
	v_mfma_f32_16x16x32_bf16 v[50:53], v[180:183], v[188:191], 0
	v_mfma_f32_16x16x32_bf16 v[38:41], v[172:175], v[226:229], 0
	v_mfma_f32_16x16x32_bf16 v[34:37], v[180:183], v[226:229], 0
	v_mfma_f32_16x16x32_bf16 v[22:25], v[172:175], v[234:237], 0
	v_mfma_f32_16x16x32_bf16 v[18:21], v[180:183], v[234:237], 0
	v_mfma_f32_16x16x32_bf16 v[4:7], v[172:175], v[242:245], 0
	v_mfma_f32_16x16x32_bf16 v[0:3], v[180:183], v[242:245], 0
	v_mfma_f32_16x16x32_bf16 v[54:57], v[176:179], v[192:195], v[54:57]
	v_mfma_f32_16x16x32_bf16 v[50:53], v[184:187], v[192:195], v[50:53]
	v_mfma_f32_16x16x32_bf16 v[38:41], v[176:179], v[230:233], v[38:41]
	v_mfma_f32_16x16x32_bf16 v[34:37], v[184:187], v[230:233], v[34:37]
	v_mfma_f32_16x16x32_bf16 v[22:25], v[176:179], v[238:241], v[22:25]
	v_mfma_f32_16x16x32_bf16 v[18:21], v[184:187], v[238:241], v[18:21]
	v_mfma_f32_16x16x32_bf16 v[4:7], v[176:179], v[246:249], v[4:7]
	v_mfma_f32_16x16x32_bf16 v[0:3], v[184:187], v[246:249], v[0:3]
	s_setprio 0
	s_barrier
	s_branch .Lgemm_mid_2
.LBB0_1241:
	s_add_u32 s3, s50, 0xfffc0080
	s_addc_u32 s52, s51, -1
	s_add_i32 s59, 0, 0x10000
	s_cmp_eq_u32 s58, 12
	s_cselect_b32 s55, s11, s52
	s_cselect_b32 s54, s12, s3
	v_add_u32_e32 v142, s59, v153
	s_cselect_b32 s53, s9, s49
	s_cselect_b32 s52, s38, s43
	s_add_i32 s3, 0, 0x14000
	ds_read_b128 v[156:159], v142
	ds_read_b128 v[160:163], v142 offset:1024
	ds_read_b128 v[164:167], v142 offset:2048
	ds_read_b128 v[168:171], v142 offset:3072
	v_add_u32_e32 v142, s3, v153
	ds_read_b128 v[172:175], v142
	ds_read_b128 v[176:179], v142 offset:1024
	ds_read_b128 v[180:183], v142 offset:2048
	ds_read_b128 v[184:187], v142 offset:3072
	s_add_i32 m0, s17, 0xc000
	ds_read_b128 v[188:191], v154
	ds_read_b128 v[192:195], v154 offset:1024
	ds_read_b128 v[226:229], v154 offset:2048
	ds_read_b128 v[230:233], v154 offset:3072
	ds_read_b128 v[234:237], v154 offset:4096
	ds_read_b128 v[238:241], v154 offset:5120
	ds_read_b128 v[242:245], v154 offset:6144
	ds_read_b128 v[246:249], v154 offset:7168
	global_load_lds_dwordx4 v140, s[50:51]
	s_add_i32 m0, s17, 0xe000
	s_nop 0
	global_load_lds_dwordx4 v138, s[50:51]
	s_waitcnt vmcnt(8)
	s_waitcnt lgkmcnt(0)
	s_barrier
	s_setprio 1
	s_waitcnt lgkmcnt(0)
	v_mfma_f32_16x16x32_bf16 v[126:129], v[156:159], v[188:191], v[126:129]
	v_mfma_f32_16x16x32_bf16 v[122:125], v[164:167], v[188:191], v[122:125]
	v_mfma_f32_16x16x32_bf16 v[110:113], v[156:159], v[226:229], v[110:113]
	v_mfma_f32_16x16x32_bf16 v[106:109], v[164:167], v[226:229], v[106:109]
	v_mfma_f32_16x16x32_bf16 v[94:97], v[156:159], v[234:237], v[94:97]
	v_mfma_f32_16x16x32_bf16 v[90:93], v[164:167], v[234:237], v[90:93]
	v_mfma_f32_16x16x32_bf16 v[78:81], v[156:159], v[242:245], v[78:81]
	v_mfma_f32_16x16x32_bf16 v[74:77], v[164:167], v[242:245], v[74:77]
	v_mfma_f32_16x16x32_bf16 v[126:129], v[160:163], v[192:195], v[126:129]
	v_mfma_f32_16x16x32_bf16 v[122:125], v[168:171], v[192:195], v[122:125]
	v_mfma_f32_16x16x32_bf16 v[110:113], v[160:163], v[230:233], v[110:113]
	v_mfma_f32_16x16x32_bf16 v[106:109], v[168:171], v[230:233], v[106:109]
	v_mfma_f32_16x16x32_bf16 v[94:97], v[160:163], v[238:241], v[94:97]
	v_mfma_f32_16x16x32_bf16 v[90:93], v[168:171], v[238:241], v[90:93]
	v_mfma_f32_16x16x32_bf16 v[78:81], v[160:163], v[246:249], v[78:81]
	v_mfma_f32_16x16x32_bf16 v[74:77], v[168:171], v[246:249], v[74:77]
	s_setprio 0
	s_setprio 1
	v_mfma_f32_16x16x32_bf16 v[118:121], v[172:175], v[188:191], v[118:121]
	v_mfma_f32_16x16x32_bf16 v[114:117], v[180:183], v[188:191], v[114:117]
	v_mfma_f32_16x16x32_bf16 v[102:105], v[172:175], v[226:229], v[102:105]
	v_mfma_f32_16x16x32_bf16 v[98:101], v[180:183], v[226:229], v[98:101]
	v_mfma_f32_16x16x32_bf16 v[86:89], v[172:175], v[234:237], v[86:89]
	v_mfma_f32_16x16x32_bf16 v[82:85], v[180:183], v[234:237], v[82:85]
	v_mfma_f32_16x16x32_bf16 v[70:73], v[172:175], v[242:245], v[70:73]
	v_mfma_f32_16x16x32_bf16 v[66:69], v[180:183], v[242:245], v[66:69]
	v_mfma_f32_16x16x32_bf16 v[118:121], v[176:179], v[192:195], v[118:121]
	v_mfma_f32_16x16x32_bf16 v[114:117], v[184:187], v[192:195], v[114:117]
	v_mfma_f32_16x16x32_bf16 v[102:105], v[176:179], v[230:233], v[102:105]
	v_mfma_f32_16x16x32_bf16 v[98:101], v[184:187], v[230:233], v[98:101]
	v_mfma_f32_16x16x32_bf16 v[86:89], v[176:179], v[238:241], v[86:89]
	v_mfma_f32_16x16x32_bf16 v[82:85], v[184:187], v[238:241], v[82:85]
	v_mfma_f32_16x16x32_bf16 v[70:73], v[176:179], v[246:249], v[70:73]
	v_mfma_f32_16x16x32_bf16 v[66:69], v[184:187], v[246:249], v[66:69]
	s_setprio 0
	s_barrier
	s_add_i32 s59, s59, s16
	v_lshl_add_u64 v[142:143], s[52:53], 0, v[132:133]
	s_mov_b32 m0, s59
	ds_read_b128 v[188:191], v154 offset:16384
	ds_read_b128 v[192:195], v154 offset:17408
	ds_read_b128 v[226:229], v154 offset:18432
	ds_read_b128 v[230:233], v154 offset:19456
	ds_read_b128 v[234:237], v154 offset:20480
	ds_read_b128 v[238:241], v154 offset:21504
	ds_read_b128 v[242:245], v154 offset:22528
	ds_read_b128 v[246:249], v154 offset:23552
	global_load_lds_dwordx4 v[142:143], off
	s_add_i32 m0, s59, 0x2000
	s_add_u32 s60, s52, 0x40000
	v_lshl_add_u64 v[150:151], s[52:53], 0, v[136:137]
	s_addc_u32 s61, s53, 0
	s_add_i32 s3, s3, s16
	global_load_lds_dwordx4 v[150:151], off
	s_mov_b32 m0, s3
	v_lshl_add_u64 v[250:251], s[54:55], 0, v[134:135]
	global_load_lds_dwordx4 v132, s[60:61]
	s_add_i32 m0, s3, 0x2000
	s_nop 0
	global_load_lds_dwordx4 v136, s[60:61]
	v_lshl_add_u64 v[196:197], s[54:55], 0, v[130:131]
	s_mov_b32 m0, s17
	s_nop 0
	global_load_lds_dwordx4 v[196:197], off
	s_mov_b32 m0, s18
	s_nop 0
	global_load_lds_dwordx4 v[250:251], off
	s_waitcnt vmcnt(8)
	s_waitcnt lgkmcnt(0)
	s_barrier
	s_setprio 1
	s_waitcnt lgkmcnt(0)
	v_mfma_f32_16x16x32_bf16 v[62:65], v[156:159], v[188:191], v[62:65]
	v_mfma_f32_16x16x32_bf16 v[58:61], v[164:167], v[188:191], v[58:61]
	v_mfma_f32_16x16x32_bf16 v[46:49], v[156:159], v[226:229], v[46:49]
	v_mfma_f32_16x16x32_bf16 v[42:45], v[164:167], v[226:229], v[42:45]
	v_mfma_f32_16x16x32_bf16 v[30:33], v[156:159], v[234:237], v[30:33]
	v_mfma_f32_16x16x32_bf16 v[26:29], v[164:167], v[234:237], v[26:29]
	v_mfma_f32_16x16x32_bf16 v[14:17], v[156:159], v[242:245], v[14:17]
	v_mfma_f32_16x16x32_bf16 v[10:13], v[164:167], v[242:245], v[10:13]
	v_mfma_f32_16x16x32_bf16 v[62:65], v[160:163], v[192:195], v[62:65]
	v_mfma_f32_16x16x32_bf16 v[58:61], v[168:171], v[192:195], v[58:61]
	v_mfma_f32_16x16x32_bf16 v[46:49], v[160:163], v[230:233], v[46:49]
	v_mfma_f32_16x16x32_bf16 v[42:45], v[168:171], v[230:233], v[42:45]
	v_mfma_f32_16x16x32_bf16 v[30:33], v[160:163], v[238:241], v[30:33]
	v_mfma_f32_16x16x32_bf16 v[26:29], v[168:171], v[238:241], v[26:29]
	v_mfma_f32_16x16x32_bf16 v[14:17], v[160:163], v[246:249], v[14:17]
	v_mfma_f32_16x16x32_bf16 v[10:13], v[168:171], v[246:249], v[10:13]
	s_setprio 0
	s_setprio 1
	v_mfma_f32_16x16x32_bf16 v[54:57], v[172:175], v[188:191], v[54:57]
	v_mfma_f32_16x16x32_bf16 v[50:53], v[180:183], v[188:191], v[50:53]
	v_mfma_f32_16x16x32_bf16 v[38:41], v[172:175], v[226:229], v[38:41]
	v_mfma_f32_16x16x32_bf16 v[34:37], v[180:183], v[226:229], v[34:37]
	v_mfma_f32_16x16x32_bf16 v[22:25], v[172:175], v[234:237], v[22:25]
	v_mfma_f32_16x16x32_bf16 v[18:21], v[180:183], v[234:237], v[18:21]
	v_mfma_f32_16x16x32_bf16 v[4:7], v[172:175], v[242:245], v[4:7]
	v_mfma_f32_16x16x32_bf16 v[0:3], v[180:183], v[242:245], v[0:3]
	v_mfma_f32_16x16x32_bf16 v[54:57], v[176:179], v[192:195], v[54:57]
	v_mfma_f32_16x16x32_bf16 v[50:53], v[184:187], v[192:195], v[50:53]
	v_mfma_f32_16x16x32_bf16 v[38:41], v[176:179], v[230:233], v[38:41]
	v_mfma_f32_16x16x32_bf16 v[34:37], v[184:187], v[230:233], v[34:37]
	v_mfma_f32_16x16x32_bf16 v[22:25], v[176:179], v[238:241], v[22:25]
	v_mfma_f32_16x16x32_bf16 v[18:21], v[184:187], v[238:241], v[18:21]
	v_mfma_f32_16x16x32_bf16 v[4:7], v[176:179], v[246:249], v[4:7]
	v_mfma_f32_16x16x32_bf16 v[0:3], v[184:187], v[246:249], v[0:3]
	s_setprio 0
	s_barrier
.Lgemm_mid_2:
	s_add_i32 s3, 0, 0x18000
	v_add_u32_e32 v144, s3, v153
	s_add_i32 s59, 0, 0x1c000
	ds_read_b128 v[156:159], v144
	ds_read_b128 v[160:163], v144 offset:1024
	ds_read_b128 v[164:167], v144 offset:2048
	ds_read_b128 v[168:171], v144 offset:3072
	v_add_u32_e32 v144, s59, v153
	ds_read_b128 v[172:175], v144
	ds_read_b128 v[176:179], v144 offset:1024
	ds_read_b128 v[180:183], v144 offset:2048
	ds_read_b128 v[184:187], v144 offset:3072
	s_add_u32 s54, s54, 0x40000
	s_addc_u32 s55, s55, 0
	s_mov_b32 m0, s20
	ds_read_b128 v[188:191], v154 offset:32768
	ds_read_b128 v[192:195], v154 offset:33792
	ds_read_b128 v[226:229], v154 offset:34816
	ds_read_b128 v[230:233], v154 offset:35840
	ds_read_b128 v[234:237], v154 offset:36864
	ds_read_b128 v[238:241], v154 offset:37888
	ds_read_b128 v[242:245], v154 offset:38912
	ds_read_b128 v[246:249], v154 offset:39936
	global_load_lds_dwordx4 v130, s[54:55]
	s_mov_b32 m0, s35
	s_nop 0
	global_load_lds_dwordx4 v134, s[54:55]
	s_waitcnt vmcnt(8)
	s_waitcnt lgkmcnt(0)
	s_barrier
	s_setprio 1
	s_waitcnt lgkmcnt(0)
	v_mfma_f32_16x16x32_bf16 v[126:129], v[156:159], v[188:191], v[126:129]
	v_mfma_f32_16x16x32_bf16 v[122:125], v[164:167], v[188:191], v[122:125]
	v_mfma_f32_16x16x32_bf16 v[110:113], v[156:159], v[226:229], v[110:113]
	v_mfma_f32_16x16x32_bf16 v[106:109], v[164:167], v[226:229], v[106:109]
	v_mfma_f32_16x16x32_bf16 v[94:97], v[156:159], v[234:237], v[94:97]
	v_mfma_f32_16x16x32_bf16 v[90:93], v[164:167], v[234:237], v[90:93]
	v_mfma_f32_16x16x32_bf16 v[78:81], v[156:159], v[242:245], v[78:81]
	v_mfma_f32_16x16x32_bf16 v[74:77], v[164:167], v[242:245], v[74:77]
	v_mfma_f32_16x16x32_bf16 v[126:129], v[160:163], v[192:195], v[126:129]
	v_mfma_f32_16x16x32_bf16 v[122:125], v[168:171], v[192:195], v[122:125]
	v_mfma_f32_16x16x32_bf16 v[110:113], v[160:163], v[230:233], v[110:113]
	v_mfma_f32_16x16x32_bf16 v[106:109], v[168:171], v[230:233], v[106:109]
	v_mfma_f32_16x16x32_bf16 v[94:97], v[160:163], v[238:241], v[94:97]
	v_mfma_f32_16x16x32_bf16 v[90:93], v[168:171], v[238:241], v[90:93]
	v_mfma_f32_16x16x32_bf16 v[78:81], v[160:163], v[246:249], v[78:81]
	v_mfma_f32_16x16x32_bf16 v[74:77], v[168:171], v[246:249], v[74:77]
	s_setprio 0
	s_setprio 1
	v_mfma_f32_16x16x32_bf16 v[118:121], v[172:175], v[188:191], v[118:121]
	v_mfma_f32_16x16x32_bf16 v[114:117], v[180:183], v[188:191], v[114:117]
	v_mfma_f32_16x16x32_bf16 v[102:105], v[172:175], v[226:229], v[102:105]
	v_mfma_f32_16x16x32_bf16 v[98:101], v[180:183], v[226:229], v[98:101]
	v_mfma_f32_16x16x32_bf16 v[86:89], v[172:175], v[234:237], v[86:89]
	v_mfma_f32_16x16x32_bf16 v[82:85], v[180:183], v[234:237], v[82:85]
	v_mfma_f32_16x16x32_bf16 v[70:73], v[172:175], v[242:245], v[70:73]
	v_mfma_f32_16x16x32_bf16 v[66:69], v[180:183], v[242:245], v[66:69]
	v_mfma_f32_16x16x32_bf16 v[118:121], v[176:179], v[192:195], v[118:121]
	v_mfma_f32_16x16x32_bf16 v[114:117], v[184:187], v[192:195], v[114:117]
	v_mfma_f32_16x16x32_bf16 v[102:105], v[176:179], v[230:233], v[102:105]
	v_mfma_f32_16x16x32_bf16 v[98:101], v[184:187], v[230:233], v[98:101]
	v_mfma_f32_16x16x32_bf16 v[86:89], v[176:179], v[238:241], v[86:89]
	v_mfma_f32_16x16x32_bf16 v[82:85], v[184:187], v[238:241], v[82:85]
	v_mfma_f32_16x16x32_bf16 v[70:73], v[176:179], v[246:249], v[70:73]
	v_mfma_f32_16x16x32_bf16 v[66:69], v[184:187], v[246:249], v[66:69]
	s_setprio 0
	s_barrier
	s_add_i32 s3, s3, s16
	v_lshl_add_u64 v[142:143], v[142:143], 0, s[96:97]
	s_mov_b32 m0, s3
	ds_read_b128 v[188:191], v154 offset:49152
	ds_read_b128 v[192:195], v154 offset:50176
	ds_read_b128 v[226:229], v154 offset:51200
	ds_read_b128 v[230:233], v154 offset:52224
	ds_read_b128 v[234:237], v154 offset:53248
	ds_read_b128 v[238:241], v154 offset:54272
	ds_read_b128 v[242:245], v154 offset:55296
	ds_read_b128 v[246:249], v154 offset:56320
	global_load_lds_dwordx4 v[142:143], off
	s_add_i32 m0, s3, 0x2000
	s_add_u32 s52, s52, 0x40080
	v_lshl_add_u64 v[142:143], v[150:151], 0, s[96:97]
	s_addc_u32 s53, s53, 0
	s_add_i32 s3, s59, s16
	global_load_lds_dwordx4 v[142:143], off
	s_mov_b32 m0, s3
	s_nop 0
	global_load_lds_dwordx4 v132, s[52:53]
	s_add_i32 m0, s3, 0x2000
	s_nop 0
	global_load_lds_dwordx4 v136, s[52:53]
	v_lshl_add_u64 v[142:143], v[196:197], 0, s[96:97]
	s_mov_b32 m0, s64
	s_nop 0
	global_load_lds_dwordx4 v[142:143], off
	v_lshl_add_u64 v[142:143], v[250:251], 0, s[96:97]
	s_mov_b32 m0, s65
	s_nop 0
	global_load_lds_dwordx4 v[142:143], off
	s_waitcnt vmcnt(8)
	s_waitcnt lgkmcnt(0)
	s_barrier
	s_setprio 1
	s_waitcnt lgkmcnt(0)
	v_mfma_f32_16x16x32_bf16 v[62:65], v[156:159], v[188:191], v[62:65]
	v_mfma_f32_16x16x32_bf16 v[58:61], v[164:167], v[188:191], v[58:61]
	v_mfma_f32_16x16x32_bf16 v[46:49], v[156:159], v[226:229], v[46:49]
	v_mfma_f32_16x16x32_bf16 v[42:45], v[164:167], v[226:229], v[42:45]
	v_mfma_f32_16x16x32_bf16 v[30:33], v[156:159], v[234:237], v[30:33]
	v_mfma_f32_16x16x32_bf16 v[26:29], v[164:167], v[234:237], v[26:29]
	v_mfma_f32_16x16x32_bf16 v[14:17], v[156:159], v[242:245], v[14:17]
	v_mfma_f32_16x16x32_bf16 v[10:13], v[164:167], v[242:245], v[10:13]
	v_mfma_f32_16x16x32_bf16 v[62:65], v[160:163], v[192:195], v[62:65]
	v_mfma_f32_16x16x32_bf16 v[58:61], v[168:171], v[192:195], v[58:61]
	v_mfma_f32_16x16x32_bf16 v[46:49], v[160:163], v[230:233], v[46:49]
	v_mfma_f32_16x16x32_bf16 v[42:45], v[168:171], v[230:233], v[42:45]
	v_mfma_f32_16x16x32_bf16 v[30:33], v[160:163], v[238:241], v[30:33]
	v_mfma_f32_16x16x32_bf16 v[26:29], v[168:171], v[238:241], v[26:29]
	v_mfma_f32_16x16x32_bf16 v[14:17], v[160:163], v[246:249], v[14:17]
	v_mfma_f32_16x16x32_bf16 v[10:13], v[168:171], v[246:249], v[10:13]
	s_setprio 0
	s_setprio 1
	v_mfma_f32_16x16x32_bf16 v[54:57], v[172:175], v[188:191], v[54:57]
	v_mfma_f32_16x16x32_bf16 v[50:53], v[180:183], v[188:191], v[50:53]
	v_mfma_f32_16x16x32_bf16 v[38:41], v[172:175], v[226:229], v[38:41]
	v_mfma_f32_16x16x32_bf16 v[34:37], v[180:183], v[226:229], v[34:37]
	v_mfma_f32_16x16x32_bf16 v[22:25], v[172:175], v[234:237], v[22:25]
	v_mfma_f32_16x16x32_bf16 v[18:21], v[180:183], v[234:237], v[18:21]
	v_mfma_f32_16x16x32_bf16 v[4:7], v[172:175], v[242:245], v[4:7]
	v_mfma_f32_16x16x32_bf16 v[0:3], v[180:183], v[242:245], v[0:3]
	v_mfma_f32_16x16x32_bf16 v[54:57], v[176:179], v[192:195], v[54:57]
	v_mfma_f32_16x16x32_bf16 v[50:53], v[184:187], v[192:195], v[50:53]
	v_mfma_f32_16x16x32_bf16 v[38:41], v[176:179], v[230:233], v[38:41]
	v_mfma_f32_16x16x32_bf16 v[34:37], v[184:187], v[230:233], v[34:37]
	v_mfma_f32_16x16x32_bf16 v[22:25], v[176:179], v[238:241], v[22:25]
	v_mfma_f32_16x16x32_bf16 v[18:21], v[184:187], v[238:241], v[18:21]
	v_mfma_f32_16x16x32_bf16 v[4:7], v[176:179], v[246:249], v[4:7]
	v_mfma_f32_16x16x32_bf16 v[0:3], v[184:187], v[246:249], v[0:3]
	s_setprio 0
	s_barrier
	s_add_i32 s58, s58, 2
	s_add_u32 s43, s43, 0x100
	s_addc_u32 s49, s49, 0
	s_add_u32 s50, s50, 0x100
	s_addc_u32 s51, s51, 0
	s_cmp_gt_u32 s58, 13
	s_cbranch_scc0 .LBB0_1241
	s_and_b64 vcc, exec, s[6:7]
	s_cbranch_vccz .LBB0_1244
	s_barrier
